# K-loops: merged vmcnt+lgkmcnt waits and setprio raised before the barrier
# speedup vs baseline: 1.0159x; 1.0030x over previous
;     __device__ __forceinline__ bool next(int i, Unit& u) const { if (i > 0 || c < first) return false; const int idx = c - first; u.pm = idx % nM; u.pn = idx / nM; return true; }
; #define PG8_STAGE(bufoff, gbase, voff) do { _Pragma("unroll") for (int _i = 0; _i < 2; ++_i) \
;         __builtin_amdgcn_global_load_lds((const unsigned*)((const char*)(gbase) + (voff)[_i]), (PG8_LAS unsigned*)(lds + (bufoff) + ldsw + _i * 8192), 16, 0, 0); } while (0)
; #define PG8_WAIT_V(n) asm volatile("s_waitcnt vmcnt(" #n ")" ::: "memory")
; #define PG8_WAIT_L(n) asm volatile("s_waitcnt lgkmcnt(" #n ")" ::: "memory")
; template <class Epi, class Sched, bool ALIGN_EPI = false, bool SP2 = false>
; __device__ __forceinline__ void gemm_phase(PG8_LAS unsigned char* lds, const Gemm g, const Sched& S, const Epi& E) {
;     ...
;         const bool has_next = S.next(ui + 1, nxt);
;         const char* nA = has_next ? (const char*)g.A + (size_t)nxt.pm * tstep : cA; const char* nB = has_next ? (const char*)g.Bt + (size_t)nxt.pn * tstep : cB;
;         for (int t = 0; t < nt; t += 2) {
;             if constexpr (Epi::HAS_MID) { if (t == Epi::MID0 || t == Epi::MID1) E.mid(acc, cur, wr, wc, fr, fq, t == Epi::MID0 ? 0 : 1); }
;             const bool last = (t == nt - 2);
;             const char* a1 = cA + (size_t)(t + 1) * kstep;
;             const char* a2 = last ? nA : cA + (size_t)(t + 2) * kstep; const char* b2 = last ? nB : cB + (size_t)(t + 2) * kstep;
;             const char* a3 = a2 + kstep; const char* b3 = b2 + kstep;
;             if (last && has_next) S.a_ready(nxt);
;             if constexpr (SP2) {
;             PG8_LDB(B0, 0, 0); PG8_LDB(B1, 0, 1); PG8_SCHED; PG8_LDA(At, 0, 0); PG8_STAGE(PG8_SA(1, 1), a1 + hstep, voffA);
;             PG8_WAIT_V(8); PG8_WAIT_L(0); PG8_BAR; PG8_MMA(0, 0, At, B0); PG8_MMA(0, 1, At, B1); PG8_BAR; PG8_SCHED;
;             PG8_LDA(At, 0, 1); PG8_STAGE(PG8_SB(0, 0), b2, voffB); PG8_STAGE(PG8_SB(0, 1), b2 + hstep, voffB); PG8_STAGE(PG8_SA(0, 0), a2, voffA);
;             PG8_WAIT_V(8); PG8_WAIT_L(0); PG8_BAR; PG8_MMA(1, 0, At, B0); PG8_MMA(1, 1, At, B1); PG8_BAR; PG8_SCHED;
;             PG8_LDB(B0, 1, 0); PG8_LDB(B1, 1, 1); PG8_SCHED; PG8_LDA(At, 1, 0); PG8_STAGE(PG8_SA(0, 1), a2 + hstep, voffA);
;             PG8_WAIT_V(8); PG8_WAIT_L(0); PG8_BAR; PG8_MMA(0, 0, At, B0); PG8_MMA(0, 1, At, B1); PG8_BAR; PG8_SCHED;
.LBB0_123:
	s_add_u32 s8, s6, 0xfff80080
	s_addc_u32 s9, s7, -1
	s_add_i32 s43, 0, 0x10000
	s_cmp_eq_u32 s42, 28
	s_cselect_b32 s23, s15, s9
	s_cselect_b32 s22, s24, s8
	s_cselect_b32 s9, s17, s41
	s_cselect_b32 s8, s25, s40
	s_add_i32 s48, 0, 0x14000
	v_add_u32_e32 v172, s43, v165
	v_add_u32_e32 v188, s48, v165
	ds_read_b128 v[156:159], v172
	ds_read_b128 v[160:163], v172 offset:1024
	ds_read_b128 v[168:171], v172 offset:2048
	ds_read_b128 v[172:175], v172 offset:3072
	ds_read_b128 v[176:179], v188
	ds_read_b128 v[180:183], v188 offset:1024
	ds_read_b128 v[184:187], v188 offset:2048
	ds_read_b128 v[188:191], v188 offset:3072
	v_lshl_add_u64 v[228:229], s[6:7], 0, v[152:153]
	s_add_i32 m0, s31, 0xc000
	ds_read_b128 v[192:195], v167
	ds_read_b128 v[196:199], v167 offset:1024
	ds_read_b128 v[200:203], v167 offset:2048
	ds_read_b128 v[204:207], v167 offset:3072
	ds_read_b128 v[208:211], v167 offset:4096
	ds_read_b128 v[212:215], v167 offset:5120
	ds_read_b128 v[216:219], v167 offset:6144
	ds_read_b128 v[224:227], v167 offset:7168
	global_load_lds_dwordx4 v[228:229], off
	v_lshl_add_u64 v[228:229], s[6:7], 0, v[154:155]
	s_add_i32 m0, s31, 0xe000
	s_nop 0
	global_load_lds_dwordx4 v[228:229], off
	s_waitcnt vmcnt(8) lgkmcnt(0)
	s_setprio 1
	s_barrier
	v_mfma_f32_16x16x32_bf16 v[144:147], v[156:159], v[192:195], v[144:147]
	v_mfma_f32_16x16x32_bf16 v[122:125], v[168:171], v[192:195], v[122:125]
	v_mfma_f32_16x16x32_bf16 v[110:113], v[156:159], v[200:203], v[110:113]
	v_mfma_f32_16x16x32_bf16 v[106:109], v[168:171], v[200:203], v[106:109]
	v_mfma_f32_16x16x32_bf16 v[94:97], v[156:159], v[208:211], v[94:97]
	v_mfma_f32_16x16x32_bf16 v[90:93], v[168:171], v[208:211], v[90:93]
	v_mfma_f32_16x16x32_bf16 v[78:81], v[156:159], v[216:219], v[78:81]
	v_mfma_f32_16x16x32_bf16 v[74:77], v[168:171], v[216:219], v[74:77]
	v_mfma_f32_16x16x32_bf16 v[144:147], v[160:163], v[196:199], v[144:147]
	v_mfma_f32_16x16x32_bf16 v[122:125], v[172:175], v[196:199], v[122:125]
	v_mfma_f32_16x16x32_bf16 v[110:113], v[160:163], v[204:207], v[110:113]
	v_mfma_f32_16x16x32_bf16 v[106:109], v[172:175], v[204:207], v[106:109]
	v_mfma_f32_16x16x32_bf16 v[94:97], v[160:163], v[212:215], v[94:97]
	v_mfma_f32_16x16x32_bf16 v[90:93], v[172:175], v[212:215], v[90:93]
	v_mfma_f32_16x16x32_bf16 v[78:81], v[160:163], v[224:227], v[78:81]
	v_mfma_f32_16x16x32_bf16 v[74:77], v[172:175], v[224:227], v[74:77]
	v_mfma_f32_16x16x32_bf16 v[118:121], v[176:179], v[192:195], v[118:121]
	v_mfma_f32_16x16x32_bf16 v[114:117], v[184:187], v[192:195], v[114:117]
	v_mfma_f32_16x16x32_bf16 v[102:105], v[176:179], v[200:203], v[102:105]
	v_mfma_f32_16x16x32_bf16 v[98:101], v[184:187], v[200:203], v[98:101]
	v_mfma_f32_16x16x32_bf16 v[86:89], v[176:179], v[208:211], v[86:89]
	v_mfma_f32_16x16x32_bf16 v[82:85], v[184:187], v[208:211], v[82:85]
	v_mfma_f32_16x16x32_bf16 v[70:73], v[176:179], v[216:219], v[70:73]
	v_mfma_f32_16x16x32_bf16 v[66:69], v[184:187], v[216:219], v[66:69]
	v_mfma_f32_16x16x32_bf16 v[118:121], v[180:183], v[196:199], v[118:121]
	v_mfma_f32_16x16x32_bf16 v[114:117], v[188:191], v[196:199], v[114:117]
	v_mfma_f32_16x16x32_bf16 v[102:105], v[180:183], v[204:207], v[102:105]
	v_mfma_f32_16x16x32_bf16 v[98:101], v[188:191], v[204:207], v[98:101]
	v_mfma_f32_16x16x32_bf16 v[86:89], v[180:183], v[212:215], v[86:89]
	v_mfma_f32_16x16x32_bf16 v[82:85], v[188:191], v[212:215], v[82:85]
	v_mfma_f32_16x16x32_bf16 v[70:73], v[180:183], v[224:227], v[70:73]
	v_mfma_f32_16x16x32_bf16 v[66:69], v[188:191], v[224:227], v[66:69]
	s_setprio 0
	s_barrier
	s_add_i32 s43, s43, s30
	v_lshl_add_u64 v[228:229], s[8:9], 0, v[0:1]
	s_mov_b32 m0, s43
	ds_read_b128 v[192:195], v167 offset:16384
	ds_read_b128 v[196:199], v167 offset:17408
	ds_read_b128 v[200:203], v167 offset:18432
	ds_read_b128 v[204:207], v167 offset:19456
	ds_read_b128 v[208:211], v167 offset:20480
	ds_read_b128 v[212:215], v167 offset:21504
	ds_read_b128 v[216:219], v167 offset:22528
	ds_read_b128 v[224:227], v167 offset:23552
	global_load_lds_dwordx4 v[228:229], off
	s_add_i32 m0, s43, 0x2000
	s_add_u32 s82, s8, 0x80000
	v_lshl_add_u64 v[230:231], s[8:9], 0, v[126:127]
	s_addc_u32 s83, s9, 0
	s_add_i32 s43, s48, s30
	global_load_lds_dwordx4 v[230:231], off
	v_lshl_add_u64 v[232:233], s[82:83], 0, v[0:1]
	s_mov_b32 m0, s43
	v_lshl_add_u64 v[244:245], s[22:23], 0, v[148:149]
	global_load_lds_dwordx4 v[232:233], off
	v_lshl_add_u64 v[232:233], s[82:83], 0, v[126:127]
	s_add_i32 m0, s43, 0x2000
	s_nop 0
	global_load_lds_dwordx4 v[232:233], off
	v_lshl_add_u64 v[232:233], s[22:23], 0, v[150:151]
	s_mov_b32 m0, s31
	s_nop 0
	global_load_lds_dwordx4 v[232:233], off
	s_mov_b32 m0, s34
	s_nop 0
	global_load_lds_dwordx4 v[244:245], off
	s_waitcnt vmcnt(8) lgkmcnt(0)
	s_setprio 1
	s_barrier
; #define PG8_STAGE(bufoff, gbase, voff) do { _Pragma("unroll") for (int _i = 0; _i < 2; ++_i) \
;         __builtin_amdgcn_global_load_lds((const unsigned*)((const char*)(gbase) + (voff)[_i]), (PG8_LAS unsigned*)(lds + (bufoff) + ldsw + _i * 8192), 16, 0, 0); } while (0)
; #define PG8_LDA(dst, b, h) do { _Pragma("unroll") for (int m = 0; m < 4; ++m) _Pragma("unroll") for (int k = 0; k < 2; ++k) dst[m][k] = *(const PG8_LAS bf16x8*)(lds + PG8_SA(b, h) + aoff + m * 2048 + k * 1024); } while (0)
; #define PG8_LDB(dst, b, h) do { _Pragma("unroll") for (int n = 0; n < 2; ++n) _Pragma("unroll") for (int k = 0; k < 2; ++k) dst[n][k] = *(const PG8_LAS bf16x8*)(lds + PG8_SB(b, h) + boff + n * 2048 + k * 1024); } while (0)
; #define PG8_MMA(ai, bj, At, Bt) do { __builtin_amdgcn_s_setprio(1); _Pragma("unroll") for (int m = 0; m < 4; ++m) _Pragma("unroll") for (int n = 0; n < 2; ++n) _Pragma("unroll") for (int k = 0; k < 2; ++k) \
;         acc[ai][bj][m][n] = __builtin_amdgcn_mfma_f32_16x16x32_bf16(Bt[n][k], At[m][k], acc[ai][bj][m][n], 0, 0, 0); __builtin_amdgcn_s_setprio(0); } while (0)
; #define PG8_WAIT_V(n) asm volatile("s_waitcnt vmcnt(" #n ")" ::: "memory")
; #define PG8_WAIT_L(n) asm volatile("s_waitcnt lgkmcnt(" #n ")" ::: "memory")
; #define PG8_BAR __builtin_amdgcn_s_barrier()
; #define PG8_SCHED __builtin_amdgcn_sched_barrier(0)
; template <class Epi, class Sched, bool ALIGN_EPI = false, bool SP2 = false>
; __device__ __forceinline__ void gemm_phase(PG8_LAS unsigned char* lds, const Gemm g, const Sched& S, const Epi& E) {
;     ...
;             PG8_WAIT_V(8); PG8_WAIT_L(0); PG8_BAR; PG8_MMA(1, 0, At, B0); PG8_MMA(1, 1, At, B1); PG8_BAR; PG8_SCHED;
;             PG8_LDB(B0, 1, 0); PG8_LDB(B1, 1, 1); PG8_SCHED; PG8_LDA(At, 1, 0); PG8_STAGE(PG8_SA(0, 1), a2 + hstep, voffA);
;             PG8_WAIT_V(8); PG8_WAIT_L(0); PG8_BAR; PG8_MMA(0, 0, At, B0); PG8_MMA(0, 1, At, B1); PG8_BAR; PG8_SCHED;
	v_mfma_f32_16x16x32_bf16 v[62:65], v[156:159], v[192:195], v[62:65]
	v_mfma_f32_16x16x32_bf16 v[58:61], v[168:171], v[192:195], v[58:61]
	v_mfma_f32_16x16x32_bf16 v[46:49], v[156:159], v[200:203], v[46:49]
	v_mfma_f32_16x16x32_bf16 v[42:45], v[168:171], v[200:203], v[42:45]
	v_mfma_f32_16x16x32_bf16 v[30:33], v[156:159], v[208:211], v[30:33]
	v_mfma_f32_16x16x32_bf16 v[26:29], v[168:171], v[208:211], v[26:29]
	v_mfma_f32_16x16x32_bf16 v[14:17], v[156:159], v[216:219], v[14:17]
	v_mfma_f32_16x16x32_bf16 v[10:13], v[168:171], v[216:219], v[10:13]
	v_mfma_f32_16x16x32_bf16 v[62:65], v[160:163], v[196:199], v[62:65]
	v_mfma_f32_16x16x32_bf16 v[58:61], v[172:175], v[196:199], v[58:61]
	v_mfma_f32_16x16x32_bf16 v[46:49], v[160:163], v[204:207], v[46:49]
	v_mfma_f32_16x16x32_bf16 v[42:45], v[172:175], v[204:207], v[42:45]
	v_mfma_f32_16x16x32_bf16 v[30:33], v[160:163], v[212:215], v[30:33]
	v_mfma_f32_16x16x32_bf16 v[26:29], v[172:175], v[212:215], v[26:29]
	v_mfma_f32_16x16x32_bf16 v[14:17], v[160:163], v[224:227], v[14:17]
	v_mfma_f32_16x16x32_bf16 v[10:13], v[172:175], v[224:227], v[10:13]
	v_mfma_f32_16x16x32_bf16 v[54:57], v[176:179], v[192:195], v[54:57]
	v_mfma_f32_16x16x32_bf16 v[50:53], v[184:187], v[192:195], v[50:53]
	v_mfma_f32_16x16x32_bf16 v[38:41], v[176:179], v[200:203], v[38:41]
	v_mfma_f32_16x16x32_bf16 v[34:37], v[184:187], v[200:203], v[34:37]
	v_mfma_f32_16x16x32_bf16 v[22:25], v[176:179], v[208:211], v[22:25]
	v_mfma_f32_16x16x32_bf16 v[18:21], v[184:187], v[208:211], v[18:21]
	v_mfma_f32_16x16x32_bf16 v[6:9], v[176:179], v[216:219], v[6:9]
	v_mfma_f32_16x16x32_bf16 v[2:5], v[184:187], v[216:219], v[2:5]
	v_mfma_f32_16x16x32_bf16 v[54:57], v[180:183], v[196:199], v[54:57]
	v_mfma_f32_16x16x32_bf16 v[50:53], v[188:191], v[196:199], v[50:53]
	v_mfma_f32_16x16x32_bf16 v[38:41], v[180:183], v[204:207], v[38:41]
	v_mfma_f32_16x16x32_bf16 v[34:37], v[188:191], v[204:207], v[34:37]
	v_mfma_f32_16x16x32_bf16 v[22:25], v[180:183], v[212:215], v[22:25]
	v_mfma_f32_16x16x32_bf16 v[18:21], v[188:191], v[212:215], v[18:21]
	v_mfma_f32_16x16x32_bf16 v[6:9], v[180:183], v[224:227], v[6:9]
	v_mfma_f32_16x16x32_bf16 v[2:5], v[188:191], v[224:227], v[2:5]
	s_setprio 0
	s_barrier
	s_add_i32 s43, 0, 0x18000
	s_add_i32 s48, 0, 0x1c000
	v_add_u32_e32 v172, s43, v165
	v_add_u32_e32 v188, s48, v165
	ds_read_b128 v[156:159], v172
	ds_read_b128 v[160:163], v172 offset:1024
	ds_read_b128 v[168:171], v172 offset:2048
	ds_read_b128 v[172:175], v172 offset:3072
	ds_read_b128 v[176:179], v188
	ds_read_b128 v[180:183], v188 offset:1024
	ds_read_b128 v[184:187], v188 offset:2048
	ds_read_b128 v[188:191], v188 offset:3072
	s_add_u32 s22, s22, 0x80000
	s_addc_u32 s23, s23, 0
	s_mov_b32 m0, s35
	v_lshl_add_u64 v[246:247], s[22:23], 0, v[150:151]
	ds_read_b128 v[192:195], v167 offset:32768
	ds_read_b128 v[196:199], v167 offset:33792
	ds_read_b128 v[200:203], v167 offset:34816
	ds_read_b128 v[204:207], v167 offset:35840
	ds_read_b128 v[208:211], v167 offset:36864
	ds_read_b128 v[212:215], v167 offset:37888
	ds_read_b128 v[216:219], v167 offset:38912
	ds_read_b128 v[224:227], v167 offset:39936
	global_load_lds_dwordx4 v[246:247], off
	v_lshl_add_u64 v[246:247], s[22:23], 0, v[148:149]
	s_mov_b32 m0, s36
	s_nop 0
	global_load_lds_dwordx4 v[246:247], off
	s_waitcnt vmcnt(8) lgkmcnt(0)
	s_setprio 1
	s_barrier
	v_mfma_f32_16x16x32_bf16 v[144:147], v[156:159], v[192:195], v[144:147]
	v_mfma_f32_16x16x32_bf16 v[122:125], v[168:171], v[192:195], v[122:125]
	v_mfma_f32_16x16x32_bf16 v[110:113], v[156:159], v[200:203], v[110:113]
	v_mfma_f32_16x16x32_bf16 v[106:109], v[168:171], v[200:203], v[106:109]
	v_mfma_f32_16x16x32_bf16 v[94:97], v[156:159], v[208:211], v[94:97]
	v_mfma_f32_16x16x32_bf16 v[90:93], v[168:171], v[208:211], v[90:93]
	v_mfma_f32_16x16x32_bf16 v[78:81], v[156:159], v[216:219], v[78:81]
	v_mfma_f32_16x16x32_bf16 v[74:77], v[168:171], v[216:219], v[74:77]
	v_mfma_f32_16x16x32_bf16 v[144:147], v[160:163], v[196:199], v[144:147]
	v_mfma_f32_16x16x32_bf16 v[122:125], v[172:175], v[196:199], v[122:125]
	v_mfma_f32_16x16x32_bf16 v[110:113], v[160:163], v[204:207], v[110:113]
	v_mfma_f32_16x16x32_bf16 v[106:109], v[172:175], v[204:207], v[106:109]
	v_mfma_f32_16x16x32_bf16 v[94:97], v[160:163], v[212:215], v[94:97]
	v_mfma_f32_16x16x32_bf16 v[90:93], v[172:175], v[212:215], v[90:93]
	v_mfma_f32_16x16x32_bf16 v[78:81], v[160:163], v[224:227], v[78:81]
	v_mfma_f32_16x16x32_bf16 v[74:77], v[172:175], v[224:227], v[74:77]
	v_mfma_f32_16x16x32_bf16 v[118:121], v[176:179], v[192:195], v[118:121]
	v_mfma_f32_16x16x32_bf16 v[114:117], v[184:187], v[192:195], v[114:117]
	v_mfma_f32_16x16x32_bf16 v[102:105], v[176:179], v[200:203], v[102:105]
	v_mfma_f32_16x16x32_bf16 v[98:101], v[184:187], v[200:203], v[98:101]
	v_mfma_f32_16x16x32_bf16 v[86:89], v[176:179], v[208:211], v[86:89]
	v_mfma_f32_16x16x32_bf16 v[82:85], v[184:187], v[208:211], v[82:85]
	v_mfma_f32_16x16x32_bf16 v[70:73], v[176:179], v[216:219], v[70:73]
	v_mfma_f32_16x16x32_bf16 v[66:69], v[184:187], v[216:219], v[66:69]
	v_mfma_f32_16x16x32_bf16 v[118:121], v[180:183], v[196:199], v[118:121]
	v_mfma_f32_16x16x32_bf16 v[114:117], v[188:191], v[196:199], v[114:117]
	v_mfma_f32_16x16x32_bf16 v[102:105], v[180:183], v[204:207], v[102:105]
	v_mfma_f32_16x16x32_bf16 v[98:101], v[188:191], v[204:207], v[98:101]
	v_mfma_f32_16x16x32_bf16 v[86:89], v[180:183], v[212:215], v[86:89]
	v_mfma_f32_16x16x32_bf16 v[82:85], v[188:191], v[212:215], v[82:85]
	v_mfma_f32_16x16x32_bf16 v[70:73], v[180:183], v[224:227], v[70:73]
	v_mfma_f32_16x16x32_bf16 v[66:69], v[188:191], v[224:227], v[66:69]
	s_setprio 0
	s_barrier
; #define PG8_STAGE(bufoff, gbase, voff) do { _Pragma("unroll") for (int _i = 0; _i < 2; ++_i) \
;         __builtin_amdgcn_global_load_lds((const unsigned*)((const char*)(gbase) + (voff)[_i]), (PG8_LAS unsigned*)(lds + (bufoff) + ldsw + _i * 8192), 16, 0, 0); } while (0)
; #define PG8_LDA(dst, b, h) do { _Pragma("unroll") for (int m = 0; m < 4; ++m) _Pragma("unroll") for (int k = 0; k < 2; ++k) dst[m][k] = *(const PG8_LAS bf16x8*)(lds + PG8_SA(b, h) + aoff + m * 2048 + k * 1024); } while (0)
; #define PG8_MMA(ai, bj, At, Bt) do { __builtin_amdgcn_s_setprio(1); _Pragma("unroll") for (int m = 0; m < 4; ++m) _Pragma("unroll") for (int n = 0; n < 2; ++n) _Pragma("unroll") for (int k = 0; k < 2; ++k) \
;         acc[ai][bj][m][n] = __builtin_amdgcn_mfma_f32_16x16x32_bf16(Bt[n][k], At[m][k], acc[ai][bj][m][n], 0, 0, 0); __builtin_amdgcn_s_setprio(0); } while (0)
; #define PG8_WAIT_V(n) asm volatile("s_waitcnt vmcnt(" #n ")" ::: "memory")
; #define PG8_WAIT_L(n) asm volatile("s_waitcnt lgkmcnt(" #n ")" ::: "memory")
; #define PG8_BAR __builtin_amdgcn_s_barrier()
; #define PG8_SCHED __builtin_amdgcn_sched_barrier(0)
; template <class Epi, class Sched, bool ALIGN_EPI = false, bool SP2 = false>
; __device__ __forceinline__ void gemm_phase(PG8_LAS unsigned char* lds, const Gemm g, const Sched& S, const Epi& E) {
;     ...
;         for (int t = 0; t < nt; t += 2) {
;     ...
;             PG8_LDA(At, 1, 1); PG8_STAGE(PG8_SB(1, 0), b3, voffB); PG8_STAGE(PG8_SB(1, 1), b3 + hstep, voffB); PG8_STAGE(PG8_SA(1, 0), a3, voffA);
;             PG8_WAIT_V(8); PG8_WAIT_L(0); PG8_BAR; PG8_MMA(1, 0, At, B0); PG8_MMA(1, 1, At, B1); PG8_BAR; PG8_SCHED;
	s_add_i32 s22, s43, s30
	v_lshl_add_u64 v[228:229], v[228:229], 0, s[64:65]
	s_mov_b32 m0, s22
	ds_read_b128 v[192:195], v167 offset:49152
	ds_read_b128 v[196:199], v167 offset:50176
	ds_read_b128 v[200:203], v167 offset:51200
	ds_read_b128 v[204:207], v167 offset:52224
	ds_read_b128 v[208:211], v167 offset:53248
	ds_read_b128 v[212:215], v167 offset:54272
	ds_read_b128 v[216:219], v167 offset:55296
	ds_read_b128 v[224:227], v167 offset:56320
	global_load_lds_dwordx4 v[228:229], off
	s_add_i32 m0, s22, 0x2000
	s_add_u32 s8, s8, 0x80080
	v_lshl_add_u64 v[228:229], v[230:231], 0, s[64:65]
	s_addc_u32 s9, s9, 0
	s_add_i32 s22, s48, s30
	global_load_lds_dwordx4 v[228:229], off
	v_lshl_add_u64 v[228:229], s[8:9], 0, v[0:1]
	s_mov_b32 m0, s22
	s_nop 0
	global_load_lds_dwordx4 v[228:229], off
	v_lshl_add_u64 v[228:229], s[8:9], 0, v[126:127]
	s_add_i32 m0, s22, 0x2000
	s_nop 0
	global_load_lds_dwordx4 v[228:229], off
	v_lshl_add_u64 v[228:229], v[232:233], 0, s[64:65]
	s_mov_b32 m0, s37
	s_nop 0
	global_load_lds_dwordx4 v[228:229], off
	v_lshl_add_u64 v[228:229], v[244:245], 0, s[64:65]
	s_mov_b32 m0, s76
	s_nop 0
	global_load_lds_dwordx4 v[228:229], off
	s_waitcnt vmcnt(8) lgkmcnt(0)
	s_setprio 1
	s_barrier
	v_mfma_f32_16x16x32_bf16 v[62:65], v[156:159], v[192:195], v[62:65]
	v_mfma_f32_16x16x32_bf16 v[58:61], v[168:171], v[192:195], v[58:61]
	v_mfma_f32_16x16x32_bf16 v[46:49], v[156:159], v[200:203], v[46:49]
	v_mfma_f32_16x16x32_bf16 v[42:45], v[168:171], v[200:203], v[42:45]
	v_mfma_f32_16x16x32_bf16 v[30:33], v[156:159], v[208:211], v[30:33]
	v_mfma_f32_16x16x32_bf16 v[26:29], v[168:171], v[208:211], v[26:29]
	v_mfma_f32_16x16x32_bf16 v[14:17], v[156:159], v[216:219], v[14:17]
	v_mfma_f32_16x16x32_bf16 v[10:13], v[168:171], v[216:219], v[10:13]
	v_mfma_f32_16x16x32_bf16 v[62:65], v[160:163], v[196:199], v[62:65]
	v_mfma_f32_16x16x32_bf16 v[58:61], v[172:175], v[196:199], v[58:61]
	v_mfma_f32_16x16x32_bf16 v[46:49], v[160:163], v[204:207], v[46:49]
	v_mfma_f32_16x16x32_bf16 v[42:45], v[172:175], v[204:207], v[42:45]
	v_mfma_f32_16x16x32_bf16 v[30:33], v[160:163], v[212:215], v[30:33]
	v_mfma_f32_16x16x32_bf16 v[26:29], v[172:175], v[212:215], v[26:29]
	v_mfma_f32_16x16x32_bf16 v[14:17], v[160:163], v[224:227], v[14:17]
	v_mfma_f32_16x16x32_bf16 v[10:13], v[172:175], v[224:227], v[10:13]
	v_mfma_f32_16x16x32_bf16 v[54:57], v[176:179], v[192:195], v[54:57]
	v_mfma_f32_16x16x32_bf16 v[50:53], v[184:187], v[192:195], v[50:53]
	v_mfma_f32_16x16x32_bf16 v[38:41], v[176:179], v[200:203], v[38:41]
	v_mfma_f32_16x16x32_bf16 v[34:37], v[184:187], v[200:203], v[34:37]
	v_mfma_f32_16x16x32_bf16 v[22:25], v[176:179], v[208:211], v[22:25]
	v_mfma_f32_16x16x32_bf16 v[18:21], v[184:187], v[208:211], v[18:21]
	v_mfma_f32_16x16x32_bf16 v[6:9], v[176:179], v[216:219], v[6:9]
	v_mfma_f32_16x16x32_bf16 v[2:5], v[184:187], v[216:219], v[2:5]
	v_mfma_f32_16x16x32_bf16 v[54:57], v[180:183], v[196:199], v[54:57]
	v_mfma_f32_16x16x32_bf16 v[50:53], v[188:191], v[196:199], v[50:53]
	v_mfma_f32_16x16x32_bf16 v[38:41], v[180:183], v[204:207], v[38:41]
	v_mfma_f32_16x16x32_bf16 v[34:37], v[188:191], v[204:207], v[34:37]
	v_mfma_f32_16x16x32_bf16 v[22:25], v[180:183], v[212:215], v[22:25]
	v_mfma_f32_16x16x32_bf16 v[18:21], v[188:191], v[212:215], v[18:21]
	v_mfma_f32_16x16x32_bf16 v[6:9], v[180:183], v[224:227], v[6:9]
	v_mfma_f32_16x16x32_bf16 v[2:5], v[188:191], v[224:227], v[2:5]
	s_setprio 0
	s_barrier
	s_add_i32 s42, s42, 2
	s_add_u32 s6, s6, 0x100
	s_addc_u32 s7, s7, 0
	s_add_u32 s40, s40, 0x100
	s_addc_u32 s41, s41, 0
	s_cmp_gt_u32 s42, 29
	s_cbranch_scc0 .LBB0_123
	s_and_b64 vcc, exec, s[12:13]
	s_cbranch_vccz .LBB0_126
	s_barrier

; #define PG8_STAGE(bufoff, gbase, voff) do { _Pragma("unroll") for (int _i = 0; _i < 2; ++_i) \
;         __builtin_amdgcn_global_load_lds((const unsigned*)((const char*)(gbase) + (voff)[_i]), (PG8_LAS unsigned*)(lds + (bufoff) + ldsw + _i * 8192), 16, 0, 0); } while (0)
; #define PG8_LDA(dst, b, h) do { _Pragma("unroll") for (int m = 0; m < 4; ++m) _Pragma("unroll") for (int k = 0; k < 2; ++k) dst[m][k] = *(const PG8_LAS bf16x8*)(lds + PG8_SA(b, h) + aoff + m * 2048 + k * 1024); } while (0)
; #define PG8_LDB(dst, b, h) do { _Pragma("unroll") for (int n = 0; n < 2; ++n) _Pragma("unroll") for (int k = 0; k < 2; ++k) dst[n][k] = *(const PG8_LAS bf16x8*)(lds + PG8_SB(b, h) + boff + n * 2048 + k * 1024); } while (0)
; #define PG8_MMA(ai, bj, At, Bt) do { __builtin_amdgcn_s_setprio(1); _Pragma("unroll") for (int m = 0; m < 4; ++m) _Pragma("unroll") for (int n = 0; n < 2; ++n) _Pragma("unroll") for (int k = 0; k < 2; ++k) \
;         acc[ai][bj][m][n] = __builtin_amdgcn_mfma_f32_16x16x32_bf16(Bt[n][k], At[m][k], acc[ai][bj][m][n], 0, 0, 0); __builtin_amdgcn_s_setprio(0); } while (0)
; #define PG8_WAIT_V(n) asm volatile("s_waitcnt vmcnt(" #n ")" ::: "memory")
; #define PG8_WAIT_L(n) asm volatile("s_waitcnt lgkmcnt(" #n ")" ::: "memory")
; template <class Epi, class Sched, bool ALIGN_EPI = false, bool SP2 = false>
; __device__ __forceinline__ void gemm_phase(PG8_LAS unsigned char* lds, const Gemm g, const Sched& S, const Epi& E) {
;     ...
;             const bool last = (t == nt - 2);
;             const char* a1 = cA + (size_t)(t + 1) * kstep;
;             const char* a2 = last ? nA : cA + (size_t)(t + 2) * kstep; const char* b2 = last ? nB : cB + (size_t)(t + 2) * kstep;
;             const char* a3 = a2 + kstep; const char* b3 = b2 + kstep;
;             if (last && has_next) S.a_ready(nxt);
;             if constexpr (SP2) {
;             PG8_LDB(B0, 0, 0); PG8_LDB(B1, 0, 1); PG8_SCHED; PG8_LDA(At, 0, 0); PG8_STAGE(PG8_SA(1, 1), a1 + hstep, voffA);
;             PG8_WAIT_V(8); PG8_WAIT_L(0); PG8_BAR; PG8_MMA(0, 0, At, B0); PG8_MMA(0, 1, At, B1); PG8_BAR; PG8_SCHED;
;             PG8_LDA(At, 0, 1); PG8_STAGE(PG8_SB(0, 0), b2, voffB); PG8_STAGE(PG8_SB(0, 1), b2 + hstep, voffB); PG8_STAGE(PG8_SA(0, 0), a2, voffA);
;             PG8_WAIT_V(8); PG8_WAIT_L(0); PG8_BAR; PG8_MMA(1, 0, At, B0); PG8_MMA(1, 1, At, B1); PG8_BAR; PG8_SCHED;
.LBB0_307:
	s_add_u32 s4, s42, s0
	s_addc_u32 s5, s43, s1
	s_add_u32 s4, s4, 0x2cc00100
	s_addc_u32 s5, s5, 0
	s_add_u32 s20, s48, s0
	s_addc_u32 s21, s67, s1
	s_add_i32 s22, 0, 0x10000
	s_cmpk_eq_i32 s0, 0xf00
	s_cselect_b32 s7, s55, s5
	s_cselect_b32 s6, s54, s4
	s_cselect_b32 s5, s53, s21
	s_cselect_b32 s4, s52, s20
	s_add_i32 s23, 0, 0x14000
	v_add_u32_e32 v172, s22, v158
	v_add_u32_e32 v188, s23, v158
	ds_read_b128 v[160:163], v172
	ds_read_b128 v[164:167], v172 offset:1024
	ds_read_b128 v[168:171], v172 offset:2048
	ds_read_b128 v[172:175], v172 offset:3072
	ds_read_b128 v[176:179], v188
	ds_read_b128 v[180:183], v188 offset:1024
	ds_read_b128 v[184:187], v188 offset:2048
	ds_read_b128 v[188:191], v188 offset:3072
	v_lshl_add_u64 v[228:229], v[152:153], 0, s[0:1]
	s_add_i32 m0, s12, 0xc000
	ds_read_b128 v[192:195], v159
	ds_read_b128 v[196:199], v159 offset:1024
	ds_read_b128 v[200:203], v159 offset:2048
	ds_read_b128 v[204:207], v159 offset:3072
	ds_read_b128 v[208:211], v159 offset:4096
	ds_read_b128 v[212:215], v159 offset:5120
	ds_read_b128 v[216:219], v159 offset:6144
	ds_read_b128 v[224:227], v159 offset:7168
	global_load_lds_dwordx4 v[228:229], off
	v_lshl_add_u64 v[228:229], v[154:155], 0, s[0:1]
	s_add_i32 m0, s12, 0xe000
	s_nop 0
	global_load_lds_dwordx4 v[228:229], off
	s_waitcnt vmcnt(8) lgkmcnt(0)
	s_setprio 1
	s_barrier
	v_mfma_f32_16x16x32_bf16 v[144:147], v[160:163], v[192:195], v[144:147]
	v_mfma_f32_16x16x32_bf16 v[122:125], v[168:171], v[192:195], v[122:125]
	v_mfma_f32_16x16x32_bf16 v[118:121], v[160:163], v[200:203], v[118:121]
	v_mfma_f32_16x16x32_bf16 v[114:117], v[168:171], v[200:203], v[114:117]
	v_mfma_f32_16x16x32_bf16 v[102:105], v[160:163], v[208:211], v[102:105]
	v_mfma_f32_16x16x32_bf16 v[98:101], v[168:171], v[208:211], v[98:101]
	v_mfma_f32_16x16x32_bf16 v[86:89], v[160:163], v[216:219], v[86:89]
	v_mfma_f32_16x16x32_bf16 v[82:85], v[168:171], v[216:219], v[82:85]
	v_mfma_f32_16x16x32_bf16 v[144:147], v[164:167], v[196:199], v[144:147]
	v_mfma_f32_16x16x32_bf16 v[122:125], v[172:175], v[196:199], v[122:125]
	v_mfma_f32_16x16x32_bf16 v[118:121], v[164:167], v[204:207], v[118:121]
	v_mfma_f32_16x16x32_bf16 v[114:117], v[172:175], v[204:207], v[114:117]
	v_mfma_f32_16x16x32_bf16 v[102:105], v[164:167], v[212:215], v[102:105]
	v_mfma_f32_16x16x32_bf16 v[98:101], v[172:175], v[212:215], v[98:101]
	v_mfma_f32_16x16x32_bf16 v[86:89], v[164:167], v[224:227], v[86:89]
	v_mfma_f32_16x16x32_bf16 v[82:85], v[172:175], v[224:227], v[82:85]
	v_mfma_f32_16x16x32_bf16 v[110:113], v[176:179], v[192:195], v[110:113]
	v_mfma_f32_16x16x32_bf16 v[106:109], v[184:187], v[192:195], v[106:109]
	v_mfma_f32_16x16x32_bf16 v[94:97], v[176:179], v[200:203], v[94:97]
	v_mfma_f32_16x16x32_bf16 v[90:93], v[184:187], v[200:203], v[90:93]
	v_mfma_f32_16x16x32_bf16 v[78:81], v[176:179], v[208:211], v[78:81]
	v_mfma_f32_16x16x32_bf16 v[74:77], v[184:187], v[208:211], v[74:77]
	v_mfma_f32_16x16x32_bf16 v[70:73], v[176:179], v[216:219], v[70:73]
	v_mfma_f32_16x16x32_bf16 v[66:69], v[184:187], v[216:219], v[66:69]
	v_mfma_f32_16x16x32_bf16 v[110:113], v[180:183], v[196:199], v[110:113]
	v_mfma_f32_16x16x32_bf16 v[106:109], v[188:191], v[196:199], v[106:109]
	v_mfma_f32_16x16x32_bf16 v[94:97], v[180:183], v[204:207], v[94:97]
	v_mfma_f32_16x16x32_bf16 v[90:93], v[188:191], v[204:207], v[90:93]
	v_mfma_f32_16x16x32_bf16 v[78:81], v[180:183], v[212:215], v[78:81]
	v_mfma_f32_16x16x32_bf16 v[74:77], v[188:191], v[212:215], v[74:77]
	v_mfma_f32_16x16x32_bf16 v[70:73], v[180:183], v[224:227], v[70:73]
	v_mfma_f32_16x16x32_bf16 v[66:69], v[188:191], v[224:227], v[66:69]
	s_setprio 0
	s_barrier
	s_add_i32 s20, s22, s9
	v_lshl_add_u64 v[228:229], s[4:5], 0, v[0:1]
	s_mov_b32 m0, s20
	ds_read_b128 v[192:195], v159 offset:16384
	ds_read_b128 v[196:199], v159 offset:17408
	ds_read_b128 v[200:203], v159 offset:18432
	ds_read_b128 v[204:207], v159 offset:19456
	ds_read_b128 v[208:211], v159 offset:20480
	ds_read_b128 v[212:215], v159 offset:21504
	ds_read_b128 v[216:219], v159 offset:22528
	ds_read_b128 v[224:227], v159 offset:23552
	global_load_lds_dwordx4 v[228:229], off
	s_add_i32 m0, s20, 0x2000
	s_add_u32 s20, s4, 0x80000
	v_lshl_add_u64 v[230:231], s[4:5], 0, v[126:127]
	s_addc_u32 s21, s5, 0
	s_add_i32 s22, s23, s9
	global_load_lds_dwordx4 v[230:231], off
	v_lshl_add_u64 v[232:233], s[20:21], 0, v[0:1]
	s_mov_b32 m0, s22
	v_lshl_add_u64 v[244:245], s[6:7], 0, v[148:149]
	global_load_lds_dwordx4 v[232:233], off
	v_lshl_add_u64 v[232:233], s[20:21], 0, v[126:127]
	s_add_i32 m0, s22, 0x2000
	s_nop 0
	global_load_lds_dwordx4 v[232:233], off
	v_lshl_add_u64 v[232:233], s[6:7], 0, v[150:151]
	s_mov_b32 m0, s12
	s_nop 0
	global_load_lds_dwordx4 v[232:233], off
	s_mov_b32 m0, s13
	s_nop 0
	global_load_lds_dwordx4 v[244:245], off
	s_waitcnt vmcnt(8) lgkmcnt(0)
	s_setprio 1
	s_barrier
; #define PG8_STAGE(bufoff, gbase, voff) do { _Pragma("unroll") for (int _i = 0; _i < 2; ++_i) \
;         __builtin_amdgcn_global_load_lds((const unsigned*)((const char*)(gbase) + (voff)[_i]), (PG8_LAS unsigned*)(lds + (bufoff) + ldsw + _i * 8192), 16, 0, 0); } while (0)
; #define PG8_LDA(dst, b, h) do { _Pragma("unroll") for (int m = 0; m < 4; ++m) _Pragma("unroll") for (int k = 0; k < 2; ++k) dst[m][k] = *(const PG8_LAS bf16x8*)(lds + PG8_SA(b, h) + aoff + m * 2048 + k * 1024); } while (0)
; #define PG8_LDB(dst, b, h) do { _Pragma("unroll") for (int n = 0; n < 2; ++n) _Pragma("unroll") for (int k = 0; k < 2; ++k) dst[n][k] = *(const PG8_LAS bf16x8*)(lds + PG8_SB(b, h) + boff + n * 2048 + k * 1024); } while (0)
; #define PG8_MMA(ai, bj, At, Bt) do { __builtin_amdgcn_s_setprio(1); _Pragma("unroll") for (int m = 0; m < 4; ++m) _Pragma("unroll") for (int n = 0; n < 2; ++n) _Pragma("unroll") for (int k = 0; k < 2; ++k) \
;         acc[ai][bj][m][n] = __builtin_amdgcn_mfma_f32_16x16x32_bf16(Bt[n][k], At[m][k], acc[ai][bj][m][n], 0, 0, 0); __builtin_amdgcn_s_setprio(0); } while (0)
; #define PG8_WAIT_V(n) asm volatile("s_waitcnt vmcnt(" #n ")" ::: "memory")
; #define PG8_WAIT_L(n) asm volatile("s_waitcnt lgkmcnt(" #n ")" ::: "memory")
; #define PG8_BAR __builtin_amdgcn_s_barrier()
; #define PG8_SCHED __builtin_amdgcn_sched_barrier(0)
; template <class Epi, class Sched, bool ALIGN_EPI = false, bool SP2 = false>
; __device__ __forceinline__ void gemm_phase(PG8_LAS unsigned char* lds, const Gemm g, const Sched& S, const Epi& E) {
;     ...
;             PG8_WAIT_V(8); PG8_WAIT_L(0); PG8_BAR; PG8_MMA(1, 0, At, B0); PG8_MMA(1, 1, At, B1); PG8_BAR; PG8_SCHED;
;             PG8_LDB(B0, 1, 0); PG8_LDB(B1, 1, 1); PG8_SCHED; PG8_LDA(At, 1, 0); PG8_STAGE(PG8_SA(0, 1), a2 + hstep, voffA);
;             PG8_WAIT_V(8); PG8_WAIT_L(0); PG8_BAR; PG8_MMA(0, 0, At, B0); PG8_MMA(0, 1, At, B1); PG8_BAR; PG8_SCHED;
	v_mfma_f32_16x16x32_bf16 v[62:65], v[160:163], v[192:195], v[62:65]
	v_mfma_f32_16x16x32_bf16 v[58:61], v[168:171], v[192:195], v[58:61]
	v_mfma_f32_16x16x32_bf16 v[54:57], v[160:163], v[200:203], v[54:57]
	v_mfma_f32_16x16x32_bf16 v[50:53], v[168:171], v[200:203], v[50:53]
	v_mfma_f32_16x16x32_bf16 v[38:41], v[160:163], v[208:211], v[38:41]
	v_mfma_f32_16x16x32_bf16 v[34:37], v[168:171], v[208:211], v[34:37]
	v_mfma_f32_16x16x32_bf16 v[22:25], v[160:163], v[216:219], v[22:25]
	v_mfma_f32_16x16x32_bf16 v[18:21], v[168:171], v[216:219], v[18:21]
	v_mfma_f32_16x16x32_bf16 v[62:65], v[164:167], v[196:199], v[62:65]
	v_mfma_f32_16x16x32_bf16 v[58:61], v[172:175], v[196:199], v[58:61]
	v_mfma_f32_16x16x32_bf16 v[54:57], v[164:167], v[204:207], v[54:57]
	v_mfma_f32_16x16x32_bf16 v[50:53], v[172:175], v[204:207], v[50:53]
	v_mfma_f32_16x16x32_bf16 v[38:41], v[164:167], v[212:215], v[38:41]
	v_mfma_f32_16x16x32_bf16 v[34:37], v[172:175], v[212:215], v[34:37]
	v_mfma_f32_16x16x32_bf16 v[22:25], v[164:167], v[224:227], v[22:25]
	v_mfma_f32_16x16x32_bf16 v[18:21], v[172:175], v[224:227], v[18:21]
	v_mfma_f32_16x16x32_bf16 v[46:49], v[176:179], v[192:195], v[46:49]
	v_mfma_f32_16x16x32_bf16 v[42:45], v[184:187], v[192:195], v[42:45]
	v_mfma_f32_16x16x32_bf16 v[30:33], v[176:179], v[200:203], v[30:33]
	v_mfma_f32_16x16x32_bf16 v[26:29], v[184:187], v[200:203], v[26:29]
	v_mfma_f32_16x16x32_bf16 v[14:17], v[176:179], v[208:211], v[14:17]
	v_mfma_f32_16x16x32_bf16 v[10:13], v[184:187], v[208:211], v[10:13]
	v_mfma_f32_16x16x32_bf16 v[6:9], v[176:179], v[216:219], v[6:9]
	v_mfma_f32_16x16x32_bf16 v[2:5], v[184:187], v[216:219], v[2:5]
	v_mfma_f32_16x16x32_bf16 v[46:49], v[180:183], v[196:199], v[46:49]
	v_mfma_f32_16x16x32_bf16 v[42:45], v[188:191], v[196:199], v[42:45]
	v_mfma_f32_16x16x32_bf16 v[30:33], v[180:183], v[204:207], v[30:33]
	v_mfma_f32_16x16x32_bf16 v[26:29], v[188:191], v[204:207], v[26:29]
	v_mfma_f32_16x16x32_bf16 v[14:17], v[180:183], v[212:215], v[14:17]
	v_mfma_f32_16x16x32_bf16 v[10:13], v[188:191], v[212:215], v[10:13]
	v_mfma_f32_16x16x32_bf16 v[6:9], v[180:183], v[224:227], v[6:9]
	v_mfma_f32_16x16x32_bf16 v[2:5], v[188:191], v[224:227], v[2:5]
	s_setprio 0
	s_barrier
	s_add_i32 s20, 0, 0x18000
	s_add_i32 s21, 0, 0x1c000
	v_add_u32_e32 v172, s20, v158
	v_add_u32_e32 v188, s21, v158
	ds_read_b128 v[160:163], v172
	ds_read_b128 v[164:167], v172 offset:1024
	ds_read_b128 v[168:171], v172 offset:2048
	ds_read_b128 v[172:175], v172 offset:3072
	ds_read_b128 v[176:179], v188
	ds_read_b128 v[180:183], v188 offset:1024
	ds_read_b128 v[184:187], v188 offset:2048
	ds_read_b128 v[188:191], v188 offset:3072
	s_add_u32 s6, s6, 0x80000
	s_addc_u32 s7, s7, 0
	s_mov_b32 m0, s14
	v_lshl_add_u64 v[246:247], s[6:7], 0, v[150:151]
	ds_read_b128 v[192:195], v159 offset:32768
	ds_read_b128 v[196:199], v159 offset:33792
	ds_read_b128 v[200:203], v159 offset:34816
	ds_read_b128 v[204:207], v159 offset:35840
	ds_read_b128 v[208:211], v159 offset:36864
	ds_read_b128 v[212:215], v159 offset:37888
	ds_read_b128 v[216:219], v159 offset:38912
	ds_read_b128 v[224:227], v159 offset:39936
	global_load_lds_dwordx4 v[246:247], off
	v_lshl_add_u64 v[246:247], s[6:7], 0, v[148:149]
	s_mov_b32 m0, s15
	s_nop 0
	global_load_lds_dwordx4 v[246:247], off
	s_waitcnt vmcnt(8) lgkmcnt(0)
	s_setprio 1
	s_barrier
	v_mfma_f32_16x16x32_bf16 v[144:147], v[160:163], v[192:195], v[144:147]
	v_mfma_f32_16x16x32_bf16 v[122:125], v[168:171], v[192:195], v[122:125]
	v_mfma_f32_16x16x32_bf16 v[118:121], v[160:163], v[200:203], v[118:121]
	v_mfma_f32_16x16x32_bf16 v[114:117], v[168:171], v[200:203], v[114:117]
	v_mfma_f32_16x16x32_bf16 v[102:105], v[160:163], v[208:211], v[102:105]
	v_mfma_f32_16x16x32_bf16 v[98:101], v[168:171], v[208:211], v[98:101]
	v_mfma_f32_16x16x32_bf16 v[86:89], v[160:163], v[216:219], v[86:89]
	v_mfma_f32_16x16x32_bf16 v[82:85], v[168:171], v[216:219], v[82:85]
	v_mfma_f32_16x16x32_bf16 v[144:147], v[164:167], v[196:199], v[144:147]
	v_mfma_f32_16x16x32_bf16 v[122:125], v[172:175], v[196:199], v[122:125]
	v_mfma_f32_16x16x32_bf16 v[118:121], v[164:167], v[204:207], v[118:121]
	v_mfma_f32_16x16x32_bf16 v[114:117], v[172:175], v[204:207], v[114:117]
	v_mfma_f32_16x16x32_bf16 v[102:105], v[164:167], v[212:215], v[102:105]
	v_mfma_f32_16x16x32_bf16 v[98:101], v[172:175], v[212:215], v[98:101]
	v_mfma_f32_16x16x32_bf16 v[86:89], v[164:167], v[224:227], v[86:89]
	v_mfma_f32_16x16x32_bf16 v[82:85], v[172:175], v[224:227], v[82:85]
	v_mfma_f32_16x16x32_bf16 v[110:113], v[176:179], v[192:195], v[110:113]
	v_mfma_f32_16x16x32_bf16 v[106:109], v[184:187], v[192:195], v[106:109]
	v_mfma_f32_16x16x32_bf16 v[94:97], v[176:179], v[200:203], v[94:97]
	v_mfma_f32_16x16x32_bf16 v[90:93], v[184:187], v[200:203], v[90:93]
	v_mfma_f32_16x16x32_bf16 v[78:81], v[176:179], v[208:211], v[78:81]
	v_mfma_f32_16x16x32_bf16 v[74:77], v[184:187], v[208:211], v[74:77]
	v_mfma_f32_16x16x32_bf16 v[70:73], v[176:179], v[216:219], v[70:73]
	v_mfma_f32_16x16x32_bf16 v[66:69], v[184:187], v[216:219], v[66:69]
	v_mfma_f32_16x16x32_bf16 v[110:113], v[180:183], v[196:199], v[110:113]
	v_mfma_f32_16x16x32_bf16 v[106:109], v[188:191], v[196:199], v[106:109]
	v_mfma_f32_16x16x32_bf16 v[94:97], v[180:183], v[204:207], v[94:97]
	v_mfma_f32_16x16x32_bf16 v[90:93], v[188:191], v[204:207], v[90:93]
	v_mfma_f32_16x16x32_bf16 v[78:81], v[180:183], v[212:215], v[78:81]
	v_mfma_f32_16x16x32_bf16 v[74:77], v[188:191], v[212:215], v[74:77]
	v_mfma_f32_16x16x32_bf16 v[70:73], v[180:183], v[224:227], v[70:73]
	v_mfma_f32_16x16x32_bf16 v[66:69], v[188:191], v[224:227], v[66:69]
	s_setprio 0
	s_barrier
; #define PG8_STAGE(bufoff, gbase, voff) do { _Pragma("unroll") for (int _i = 0; _i < 2; ++_i) \
;         __builtin_amdgcn_global_load_lds((const unsigned*)((const char*)(gbase) + (voff)[_i]), (PG8_LAS unsigned*)(lds + (bufoff) + ldsw + _i * 8192), 16, 0, 0); } while (0)
; #define PG8_LDA(dst, b, h) do { _Pragma("unroll") for (int m = 0; m < 4; ++m) _Pragma("unroll") for (int k = 0; k < 2; ++k) dst[m][k] = *(const PG8_LAS bf16x8*)(lds + PG8_SA(b, h) + aoff + m * 2048 + k * 1024); } while (0)
; #define PG8_MMA(ai, bj, At, Bt) do { __builtin_amdgcn_s_setprio(1); _Pragma("unroll") for (int m = 0; m < 4; ++m) _Pragma("unroll") for (int n = 0; n < 2; ++n) _Pragma("unroll") for (int k = 0; k < 2; ++k) \
;         acc[ai][bj][m][n] = __builtin_amdgcn_mfma_f32_16x16x32_bf16(Bt[n][k], At[m][k], acc[ai][bj][m][n], 0, 0, 0); __builtin_amdgcn_s_setprio(0); } while (0)
; #define PG8_WAIT_V(n) asm volatile("s_waitcnt vmcnt(" #n ")" ::: "memory")
; #define PG8_WAIT_L(n) asm volatile("s_waitcnt lgkmcnt(" #n ")" ::: "memory")
; #define PG8_BAR __builtin_amdgcn_s_barrier()
; #define PG8_SCHED __builtin_amdgcn_sched_barrier(0)
; template <class Epi, class Sched, bool ALIGN_EPI = false, bool SP2 = false>
; __device__ __forceinline__ void gemm_phase(PG8_LAS unsigned char* lds, const Gemm g, const Sched& S, const Epi& E) {
;     ...
;             PG8_LDA(At, 1, 1); PG8_STAGE(PG8_SB(1, 0), b3, voffB); PG8_STAGE(PG8_SB(1, 1), b3 + hstep, voffB); PG8_STAGE(PG8_SA(1, 0), a3, voffA);
;             PG8_WAIT_V(8); PG8_WAIT_L(0); PG8_BAR; PG8_MMA(1, 0, At, B0); PG8_MMA(1, 1, At, B1); PG8_BAR; PG8_SCHED;
	s_add_i32 s6, s20, s9
	v_lshl_add_u64 v[228:229], v[228:229], 0, s[64:65]
	s_mov_b32 m0, s6
	ds_read_b128 v[192:195], v159 offset:49152
	ds_read_b128 v[196:199], v159 offset:50176
	ds_read_b128 v[200:203], v159 offset:51200
	ds_read_b128 v[204:207], v159 offset:52224
	ds_read_b128 v[208:211], v159 offset:53248
	ds_read_b128 v[212:215], v159 offset:54272
	ds_read_b128 v[216:219], v159 offset:55296
	ds_read_b128 v[224:227], v159 offset:56320
	global_load_lds_dwordx4 v[228:229], off
	s_add_i32 m0, s6, 0x2000
	s_add_u32 s4, s4, 0x80080
	v_lshl_add_u64 v[228:229], v[230:231], 0, s[64:65]
	s_addc_u32 s5, s5, 0
	s_add_i32 s6, s21, s9
	global_load_lds_dwordx4 v[228:229], off
	v_lshl_add_u64 v[228:229], s[4:5], 0, v[0:1]
	s_mov_b32 m0, s6
	s_nop 0
	global_load_lds_dwordx4 v[228:229], off
	v_lshl_add_u64 v[228:229], s[4:5], 0, v[126:127]
	s_add_i32 m0, s6, 0x2000
	s_nop 0
	global_load_lds_dwordx4 v[228:229], off
	v_lshl_add_u64 v[228:229], v[232:233], 0, s[64:65]
	s_mov_b32 m0, s17
	s_nop 0
	global_load_lds_dwordx4 v[228:229], off
	v_lshl_add_u64 v[228:229], v[244:245], 0, s[64:65]
	s_mov_b32 m0, s18
	s_nop 0
	global_load_lds_dwordx4 v[228:229], off
	s_waitcnt vmcnt(8) lgkmcnt(0)
	s_setprio 1
	s_barrier
	v_mfma_f32_16x16x32_bf16 v[62:65], v[160:163], v[192:195], v[62:65]
	v_mfma_f32_16x16x32_bf16 v[58:61], v[168:171], v[192:195], v[58:61]
	v_mfma_f32_16x16x32_bf16 v[54:57], v[160:163], v[200:203], v[54:57]
	v_mfma_f32_16x16x32_bf16 v[50:53], v[168:171], v[200:203], v[50:53]
	v_mfma_f32_16x16x32_bf16 v[38:41], v[160:163], v[208:211], v[38:41]
	v_mfma_f32_16x16x32_bf16 v[34:37], v[168:171], v[208:211], v[34:37]
	v_mfma_f32_16x16x32_bf16 v[22:25], v[160:163], v[216:219], v[22:25]
	v_mfma_f32_16x16x32_bf16 v[18:21], v[168:171], v[216:219], v[18:21]
	v_mfma_f32_16x16x32_bf16 v[62:65], v[164:167], v[196:199], v[62:65]
	v_mfma_f32_16x16x32_bf16 v[58:61], v[172:175], v[196:199], v[58:61]
	v_mfma_f32_16x16x32_bf16 v[54:57], v[164:167], v[204:207], v[54:57]
	v_mfma_f32_16x16x32_bf16 v[50:53], v[172:175], v[204:207], v[50:53]
	v_mfma_f32_16x16x32_bf16 v[38:41], v[164:167], v[212:215], v[38:41]
	v_mfma_f32_16x16x32_bf16 v[34:37], v[172:175], v[212:215], v[34:37]
	v_mfma_f32_16x16x32_bf16 v[22:25], v[164:167], v[224:227], v[22:25]
	v_mfma_f32_16x16x32_bf16 v[18:21], v[172:175], v[224:227], v[18:21]
	v_mfma_f32_16x16x32_bf16 v[46:49], v[176:179], v[192:195], v[46:49]
	v_mfma_f32_16x16x32_bf16 v[42:45], v[184:187], v[192:195], v[42:45]
	v_mfma_f32_16x16x32_bf16 v[30:33], v[176:179], v[200:203], v[30:33]
	v_mfma_f32_16x16x32_bf16 v[26:29], v[184:187], v[200:203], v[26:29]
	v_mfma_f32_16x16x32_bf16 v[14:17], v[176:179], v[208:211], v[14:17]
	v_mfma_f32_16x16x32_bf16 v[10:13], v[184:187], v[208:211], v[10:13]
	v_mfma_f32_16x16x32_bf16 v[6:9], v[176:179], v[216:219], v[6:9]
	v_mfma_f32_16x16x32_bf16 v[2:5], v[184:187], v[216:219], v[2:5]
	v_mfma_f32_16x16x32_bf16 v[46:49], v[180:183], v[196:199], v[46:49]
	v_mfma_f32_16x16x32_bf16 v[42:45], v[188:191], v[196:199], v[42:45]
	v_mfma_f32_16x16x32_bf16 v[30:33], v[180:183], v[204:207], v[30:33]
	v_mfma_f32_16x16x32_bf16 v[26:29], v[188:191], v[204:207], v[26:29]
	v_mfma_f32_16x16x32_bf16 v[14:17], v[180:183], v[212:215], v[14:17]
	v_mfma_f32_16x16x32_bf16 v[10:13], v[188:191], v[212:215], v[10:13]
	v_mfma_f32_16x16x32_bf16 v[6:9], v[180:183], v[224:227], v[6:9]
	v_mfma_f32_16x16x32_bf16 v[2:5], v[188:191], v[224:227], v[2:5]
	s_setprio 0
	s_barrier
	s_add_i32 s19, s19, 2
	s_add_u32 s0, s0, 0x100
	s_addc_u32 s1, s1, 0
	s_cmp_gt_u32 s19, 29
	s_cbranch_scc0 .LBB0_307
	s_cmpk_lt_u32 s8, 0x100
	s_cbranch_scc0 .LBB0_310
	s_barrier

;     __device__ __forceinline__ bool next(int i, Unit& u) const { if (i > 0 || c < first) return false; const int idx = c - first; u.pm = idx % nM; u.pn = idx / nM; return true; }
; #define PG8_STAGE(bufoff, gbase, voff) do { _Pragma("unroll") for (int _i = 0; _i < 2; ++_i) \
;         __builtin_amdgcn_global_load_lds((const unsigned*)((const char*)(gbase) + (voff)[_i]), (PG8_LAS unsigned*)(lds + (bufoff) + ldsw + _i * 8192), 16, 0, 0); } while (0)
; #define PG8_LDA(dst, b, h) do { _Pragma("unroll") for (int m = 0; m < 4; ++m) _Pragma("unroll") for (int k = 0; k < 2; ++k) dst[m][k] = *(const PG8_LAS bf16x8*)(lds + PG8_SA(b, h) + aoff + m * 2048 + k * 1024); } while (0)
; #define PG8_WAIT_V(n) asm volatile("s_waitcnt vmcnt(" #n ")" ::: "memory")
; #define PG8_WAIT_L(n) asm volatile("s_waitcnt lgkmcnt(" #n ")" ::: "memory")
; #define PG8_BAR __builtin_amdgcn_s_barrier()
; template <class Epi, class Sched, bool ALIGN_EPI = false, bool SP2 = false>
; __device__ __forceinline__ void gemm_phase(PG8_LAS unsigned char* lds, const Gemm g, const Sched& S, const Epi& E) {
;     ...
;         const bool has_next = S.next(ui + 1, nxt);
;         const char* nA = has_next ? (const char*)g.A + (size_t)nxt.pm * tstep : cA; const char* nB = has_next ? (const char*)g.Bt + (size_t)nxt.pn * tstep : cB;
;         for (int t = 0; t < nt; t += 2) {
;             if constexpr (Epi::HAS_MID) { if (t == Epi::MID0 || t == Epi::MID1) E.mid(acc, cur, wr, wc, fr, fq, t == Epi::MID0 ? 0 : 1); }
;             const bool last = (t == nt - 2);
;             const char* a1 = cA + (size_t)(t + 1) * kstep;
;             const char* a2 = last ? nA : cA + (size_t)(t + 2) * kstep; const char* b2 = last ? nB : cB + (size_t)(t + 2) * kstep;
;             const char* a3 = a2 + kstep; const char* b3 = b2 + kstep;
;             if (last && has_next) S.a_ready(nxt);
;             if constexpr (SP2) {
;             PG8_LDB(B0, 0, 0); PG8_LDB(B1, 0, 1); PG8_SCHED; PG8_LDA(At, 0, 0); PG8_STAGE(PG8_SA(1, 1), a1 + hstep, voffA);
;             PG8_WAIT_V(8); PG8_WAIT_L(0); PG8_BAR; PG8_MMA(0, 0, At, B0); PG8_MMA(0, 1, At, B1); PG8_BAR; PG8_SCHED;
;             PG8_LDA(At, 0, 1); PG8_STAGE(PG8_SB(0, 0), b2, voffB); PG8_STAGE(PG8_SB(0, 1), b2 + hstep, voffB); PG8_STAGE(PG8_SA(0, 0), a2, voffA);
;             PG8_WAIT_V(8); PG8_WAIT_L(0); PG8_BAR; PG8_MMA(1, 0, At, B0); PG8_MMA(1, 1, At, B1); PG8_BAR; PG8_SCHED;
.LBB0_733:
	s_add_u32 s22, s18, s20
	s_addc_u32 s23, s19, s21
	s_add_u32 s22, s22, 0x100
	s_addc_u32 s23, s23, 0
	s_add_u32 s26, s86, s20
	s_addc_u32 s27, s87, s21
	s_add_i32 s40, 0, 0x10000
	s_cmpk_eq_i32 s20, 0xf00
	s_cselect_b32 s25, s13, s23
	s_cselect_b32 s24, s82, s22
	s_cselect_b32 s23, s9, s27
	s_cselect_b32 s22, s83, s26
	s_add_i32 s41, 0, 0x14000
	v_add_u32_e32 v160, s40, v245
	v_add_u32_e32 v176, s41, v245
	ds_read_b128 v[148:151], v160
	ds_read_b128 v[152:155], v160 offset:1024
	ds_read_b128 v[156:159], v160 offset:2048
	ds_read_b128 v[160:163], v160 offset:3072
	ds_read_b128 v[164:167], v176
	ds_read_b128 v[168:171], v176 offset:1024
	ds_read_b128 v[172:175], v176 offset:2048
	ds_read_b128 v[176:179], v176 offset:3072
	v_lshl_add_u64 v[232:233], v[228:229], 0, s[20:21]
	s_add_i32 m0, s31, 0xc000
	ds_read_b128 v[180:183], v247
	ds_read_b128 v[184:187], v247 offset:1024
	ds_read_b128 v[188:191], v247 offset:2048
	ds_read_b128 v[192:195], v247 offset:3072
	ds_read_b128 v[196:199], v247 offset:4096
	ds_read_b128 v[200:203], v247 offset:5120
	ds_read_b128 v[204:207], v247 offset:6144
	ds_read_b128 v[208:211], v247 offset:7168
	global_load_lds_dwordx4 v[232:233], off
	v_lshl_add_u64 v[232:233], v[230:231], 0, s[20:21]
	s_add_i32 m0, s31, 0xe000
	s_nop 0
	global_load_lds_dwordx4 v[232:233], off
	s_waitcnt vmcnt(8) lgkmcnt(0)
	s_setprio 1
	s_barrier
	v_mfma_f32_16x16x32_bf16 v[144:147], v[148:151], v[180:183], v[144:147]
	v_mfma_f32_16x16x32_bf16 v[122:125], v[156:159], v[180:183], v[122:125]
	v_mfma_f32_16x16x32_bf16 v[110:113], v[148:151], v[188:191], v[110:113]
	v_mfma_f32_16x16x32_bf16 v[106:109], v[156:159], v[188:191], v[106:109]
	v_mfma_f32_16x16x32_bf16 v[94:97], v[148:151], v[196:199], v[94:97]
	v_mfma_f32_16x16x32_bf16 v[90:93], v[156:159], v[196:199], v[90:93]
	v_mfma_f32_16x16x32_bf16 v[78:81], v[148:151], v[204:207], v[78:81]
	v_mfma_f32_16x16x32_bf16 v[74:77], v[156:159], v[204:207], v[74:77]
	v_mfma_f32_16x16x32_bf16 v[144:147], v[152:155], v[184:187], v[144:147]
	v_mfma_f32_16x16x32_bf16 v[122:125], v[160:163], v[184:187], v[122:125]
	v_mfma_f32_16x16x32_bf16 v[110:113], v[152:155], v[192:195], v[110:113]
	v_mfma_f32_16x16x32_bf16 v[106:109], v[160:163], v[192:195], v[106:109]
	v_mfma_f32_16x16x32_bf16 v[94:97], v[152:155], v[200:203], v[94:97]
	v_mfma_f32_16x16x32_bf16 v[90:93], v[160:163], v[200:203], v[90:93]
	v_mfma_f32_16x16x32_bf16 v[78:81], v[152:155], v[208:211], v[78:81]
	v_mfma_f32_16x16x32_bf16 v[74:77], v[160:163], v[208:211], v[74:77]
	v_mfma_f32_16x16x32_bf16 v[118:121], v[164:167], v[180:183], v[118:121]
	v_mfma_f32_16x16x32_bf16 v[114:117], v[172:175], v[180:183], v[114:117]
	v_mfma_f32_16x16x32_bf16 v[102:105], v[164:167], v[188:191], v[102:105]
	v_mfma_f32_16x16x32_bf16 v[98:101], v[172:175], v[188:191], v[98:101]
	v_mfma_f32_16x16x32_bf16 v[86:89], v[164:167], v[196:199], v[86:89]
	v_mfma_f32_16x16x32_bf16 v[82:85], v[172:175], v[196:199], v[82:85]
	v_mfma_f32_16x16x32_bf16 v[70:73], v[164:167], v[204:207], v[70:73]
	v_mfma_f32_16x16x32_bf16 v[66:69], v[172:175], v[204:207], v[66:69]
	v_mfma_f32_16x16x32_bf16 v[118:121], v[168:171], v[184:187], v[118:121]
	v_mfma_f32_16x16x32_bf16 v[114:117], v[176:179], v[184:187], v[114:117]
	v_mfma_f32_16x16x32_bf16 v[102:105], v[168:171], v[192:195], v[102:105]
	v_mfma_f32_16x16x32_bf16 v[98:101], v[176:179], v[192:195], v[98:101]
	v_mfma_f32_16x16x32_bf16 v[86:89], v[168:171], v[200:203], v[86:89]
	v_mfma_f32_16x16x32_bf16 v[82:85], v[176:179], v[200:203], v[82:85]
	v_mfma_f32_16x16x32_bf16 v[70:73], v[168:171], v[208:211], v[70:73]
	v_mfma_f32_16x16x32_bf16 v[66:69], v[176:179], v[208:211], v[66:69]
	s_setprio 0
	s_barrier
	s_add_i32 s26, s40, s30
	v_lshl_add_u64 v[232:233], s[22:23], 0, v[0:1]
	s_mov_b32 m0, s26
	ds_read_b128 v[180:183], v247 offset:16384
	ds_read_b128 v[184:187], v247 offset:17408
	ds_read_b128 v[188:191], v247 offset:18432
	ds_read_b128 v[192:195], v247 offset:19456
	ds_read_b128 v[196:199], v247 offset:20480
	ds_read_b128 v[200:203], v247 offset:21504
	ds_read_b128 v[204:207], v247 offset:22528
	ds_read_b128 v[208:211], v247 offset:23552
	global_load_lds_dwordx4 v[232:233], off
	s_add_i32 m0, s26, 0x2000
	s_add_u32 s26, s22, 0x80000
	v_lshl_add_u64 v[248:249], s[22:23], 0, v[126:127]
	s_addc_u32 s27, s23, 0
	s_add_i32 s40, s41, s30
	global_load_lds_dwordx4 v[248:249], off
	v_lshl_add_u64 v[250:251], s[26:27], 0, v[0:1]
	s_mov_b32 m0, s40
	v_lshl_add_u64 v[220:221], s[24:25], 0, v[212:213]
	global_load_lds_dwordx4 v[250:251], off
	v_lshl_add_u64 v[250:251], s[26:27], 0, v[126:127]
	s_add_i32 m0, s40, 0x2000
	s_nop 0
	global_load_lds_dwordx4 v[250:251], off
	v_lshl_add_u64 v[250:251], s[24:25], 0, v[214:215]
	s_mov_b32 m0, s31
	s_nop 0
	global_load_lds_dwordx4 v[250:251], off
	s_mov_b32 m0, s34
	s_nop 0
	global_load_lds_dwordx4 v[220:221], off
	s_waitcnt vmcnt(8) lgkmcnt(0)
	s_setprio 1
	s_barrier
; #define PG8_STAGE(bufoff, gbase, voff) do { _Pragma("unroll") for (int _i = 0; _i < 2; ++_i) \
;         __builtin_amdgcn_global_load_lds((const unsigned*)((const char*)(gbase) + (voff)[_i]), (PG8_LAS unsigned*)(lds + (bufoff) + ldsw + _i * 8192), 16, 0, 0); } while (0)
; #define PG8_LDA(dst, b, h) do { _Pragma("unroll") for (int m = 0; m < 4; ++m) _Pragma("unroll") for (int k = 0; k < 2; ++k) dst[m][k] = *(const PG8_LAS bf16x8*)(lds + PG8_SA(b, h) + aoff + m * 2048 + k * 1024); } while (0)
; #define PG8_LDB(dst, b, h) do { _Pragma("unroll") for (int n = 0; n < 2; ++n) _Pragma("unroll") for (int k = 0; k < 2; ++k) dst[n][k] = *(const PG8_LAS bf16x8*)(lds + PG8_SB(b, h) + boff + n * 2048 + k * 1024); } while (0)
; #define PG8_MMA(ai, bj, At, Bt) do { __builtin_amdgcn_s_setprio(1); _Pragma("unroll") for (int m = 0; m < 4; ++m) _Pragma("unroll") for (int n = 0; n < 2; ++n) _Pragma("unroll") for (int k = 0; k < 2; ++k) \
;         acc[ai][bj][m][n] = __builtin_amdgcn_mfma_f32_16x16x32_bf16(Bt[n][k], At[m][k], acc[ai][bj][m][n], 0, 0, 0); __builtin_amdgcn_s_setprio(0); } while (0)
; #define PG8_WAIT_V(n) asm volatile("s_waitcnt vmcnt(" #n ")" ::: "memory")
; #define PG8_WAIT_L(n) asm volatile("s_waitcnt lgkmcnt(" #n ")" ::: "memory")
; #define PG8_BAR __builtin_amdgcn_s_barrier()
; #define PG8_SCHED __builtin_amdgcn_sched_barrier(0)
; template <class Epi, class Sched, bool ALIGN_EPI = false, bool SP2 = false>
; __device__ __forceinline__ void gemm_phase(PG8_LAS unsigned char* lds, const Gemm g, const Sched& S, const Epi& E) {
;     ...
;             PG8_WAIT_V(8); PG8_WAIT_L(0); PG8_BAR; PG8_MMA(1, 0, At, B0); PG8_MMA(1, 1, At, B1); PG8_BAR; PG8_SCHED;
;             PG8_LDB(B0, 1, 0); PG8_LDB(B1, 1, 1); PG8_SCHED; PG8_LDA(At, 1, 0); PG8_STAGE(PG8_SA(0, 1), a2 + hstep, voffA);
;             PG8_WAIT_V(8); PG8_WAIT_L(0); PG8_BAR; PG8_MMA(0, 0, At, B0); PG8_MMA(0, 1, At, B1); PG8_BAR; PG8_SCHED;
	v_mfma_f32_16x16x32_bf16 v[62:65], v[148:151], v[180:183], v[62:65]
	v_mfma_f32_16x16x32_bf16 v[58:61], v[156:159], v[180:183], v[58:61]
	v_mfma_f32_16x16x32_bf16 v[46:49], v[148:151], v[188:191], v[46:49]
	v_mfma_f32_16x16x32_bf16 v[42:45], v[156:159], v[188:191], v[42:45]
	v_mfma_f32_16x16x32_bf16 v[30:33], v[148:151], v[196:199], v[30:33]
	v_mfma_f32_16x16x32_bf16 v[26:29], v[156:159], v[196:199], v[26:29]
	v_mfma_f32_16x16x32_bf16 v[14:17], v[148:151], v[204:207], v[14:17]
	v_mfma_f32_16x16x32_bf16 v[10:13], v[156:159], v[204:207], v[10:13]
	v_mfma_f32_16x16x32_bf16 v[62:65], v[152:155], v[184:187], v[62:65]
	v_mfma_f32_16x16x32_bf16 v[58:61], v[160:163], v[184:187], v[58:61]
	v_mfma_f32_16x16x32_bf16 v[46:49], v[152:155], v[192:195], v[46:49]
	v_mfma_f32_16x16x32_bf16 v[42:45], v[160:163], v[192:195], v[42:45]
	v_mfma_f32_16x16x32_bf16 v[30:33], v[152:155], v[200:203], v[30:33]
	v_mfma_f32_16x16x32_bf16 v[26:29], v[160:163], v[200:203], v[26:29]
	v_mfma_f32_16x16x32_bf16 v[14:17], v[152:155], v[208:211], v[14:17]
	v_mfma_f32_16x16x32_bf16 v[10:13], v[160:163], v[208:211], v[10:13]
	v_mfma_f32_16x16x32_bf16 v[54:57], v[164:167], v[180:183], v[54:57]
	v_mfma_f32_16x16x32_bf16 v[50:53], v[172:175], v[180:183], v[50:53]
	v_mfma_f32_16x16x32_bf16 v[38:41], v[164:167], v[188:191], v[38:41]
	v_mfma_f32_16x16x32_bf16 v[34:37], v[172:175], v[188:191], v[34:37]
	v_mfma_f32_16x16x32_bf16 v[22:25], v[164:167], v[196:199], v[22:25]
	v_mfma_f32_16x16x32_bf16 v[18:21], v[172:175], v[196:199], v[18:21]
	v_mfma_f32_16x16x32_bf16 v[6:9], v[164:167], v[204:207], v[6:9]
	v_mfma_f32_16x16x32_bf16 v[2:5], v[172:175], v[204:207], v[2:5]
	v_mfma_f32_16x16x32_bf16 v[54:57], v[168:171], v[184:187], v[54:57]
	v_mfma_f32_16x16x32_bf16 v[50:53], v[176:179], v[184:187], v[50:53]
	v_mfma_f32_16x16x32_bf16 v[38:41], v[168:171], v[192:195], v[38:41]
	v_mfma_f32_16x16x32_bf16 v[34:37], v[176:179], v[192:195], v[34:37]
	v_mfma_f32_16x16x32_bf16 v[22:25], v[168:171], v[200:203], v[22:25]
	v_mfma_f32_16x16x32_bf16 v[18:21], v[176:179], v[200:203], v[18:21]
	v_mfma_f32_16x16x32_bf16 v[6:9], v[168:171], v[208:211], v[6:9]
	v_mfma_f32_16x16x32_bf16 v[2:5], v[176:179], v[208:211], v[2:5]
	s_setprio 0
	s_barrier
	s_add_i32 s26, 0, 0x18000
	s_add_i32 s27, 0, 0x1c000
	v_add_u32_e32 v160, s26, v245
	v_add_u32_e32 v176, s27, v245
	ds_read_b128 v[148:151], v160
	ds_read_b128 v[152:155], v160 offset:1024
	ds_read_b128 v[156:159], v160 offset:2048
	ds_read_b128 v[160:163], v160 offset:3072
	ds_read_b128 v[164:167], v176
	ds_read_b128 v[168:171], v176 offset:1024
	ds_read_b128 v[172:175], v176 offset:2048
	ds_read_b128 v[176:179], v176 offset:3072
	s_add_u32 s24, s24, 0x80000
	s_addc_u32 s25, s25, 0
	s_mov_b32 m0, s35
	v_lshl_add_u64 v[222:223], s[24:25], 0, v[214:215]
	ds_read_b128 v[180:183], v247 offset:32768
	ds_read_b128 v[184:187], v247 offset:33792
	ds_read_b128 v[188:191], v247 offset:34816
	ds_read_b128 v[192:195], v247 offset:35840
	ds_read_b128 v[196:199], v247 offset:36864
	ds_read_b128 v[200:203], v247 offset:37888
	ds_read_b128 v[204:207], v247 offset:38912
	ds_read_b128 v[208:211], v247 offset:39936
	global_load_lds_dwordx4 v[222:223], off
	v_lshl_add_u64 v[222:223], s[24:25], 0, v[212:213]
	s_mov_b32 m0, s36
	s_nop 0
	global_load_lds_dwordx4 v[222:223], off
	s_waitcnt vmcnt(8) lgkmcnt(0)
	s_setprio 1
	s_barrier
	v_mfma_f32_16x16x32_bf16 v[144:147], v[148:151], v[180:183], v[144:147]
	v_mfma_f32_16x16x32_bf16 v[122:125], v[156:159], v[180:183], v[122:125]
	v_mfma_f32_16x16x32_bf16 v[110:113], v[148:151], v[188:191], v[110:113]
	v_mfma_f32_16x16x32_bf16 v[106:109], v[156:159], v[188:191], v[106:109]
	v_mfma_f32_16x16x32_bf16 v[94:97], v[148:151], v[196:199], v[94:97]
	v_mfma_f32_16x16x32_bf16 v[90:93], v[156:159], v[196:199], v[90:93]
	v_mfma_f32_16x16x32_bf16 v[78:81], v[148:151], v[204:207], v[78:81]
	v_mfma_f32_16x16x32_bf16 v[74:77], v[156:159], v[204:207], v[74:77]
	v_mfma_f32_16x16x32_bf16 v[144:147], v[152:155], v[184:187], v[144:147]
	v_mfma_f32_16x16x32_bf16 v[122:125], v[160:163], v[184:187], v[122:125]
	v_mfma_f32_16x16x32_bf16 v[110:113], v[152:155], v[192:195], v[110:113]
	v_mfma_f32_16x16x32_bf16 v[106:109], v[160:163], v[192:195], v[106:109]
	v_mfma_f32_16x16x32_bf16 v[94:97], v[152:155], v[200:203], v[94:97]
	v_mfma_f32_16x16x32_bf16 v[90:93], v[160:163], v[200:203], v[90:93]
	v_mfma_f32_16x16x32_bf16 v[78:81], v[152:155], v[208:211], v[78:81]
	v_mfma_f32_16x16x32_bf16 v[74:77], v[160:163], v[208:211], v[74:77]
	v_mfma_f32_16x16x32_bf16 v[118:121], v[164:167], v[180:183], v[118:121]
	v_mfma_f32_16x16x32_bf16 v[114:117], v[172:175], v[180:183], v[114:117]
	v_mfma_f32_16x16x32_bf16 v[102:105], v[164:167], v[188:191], v[102:105]
	v_mfma_f32_16x16x32_bf16 v[98:101], v[172:175], v[188:191], v[98:101]
	v_mfma_f32_16x16x32_bf16 v[86:89], v[164:167], v[196:199], v[86:89]
	v_mfma_f32_16x16x32_bf16 v[82:85], v[172:175], v[196:199], v[82:85]
	v_mfma_f32_16x16x32_bf16 v[70:73], v[164:167], v[204:207], v[70:73]
	v_mfma_f32_16x16x32_bf16 v[66:69], v[172:175], v[204:207], v[66:69]
	v_mfma_f32_16x16x32_bf16 v[118:121], v[168:171], v[184:187], v[118:121]
	v_mfma_f32_16x16x32_bf16 v[114:117], v[176:179], v[184:187], v[114:117]
	v_mfma_f32_16x16x32_bf16 v[102:105], v[168:171], v[192:195], v[102:105]
	v_mfma_f32_16x16x32_bf16 v[98:101], v[176:179], v[192:195], v[98:101]
	v_mfma_f32_16x16x32_bf16 v[86:89], v[168:171], v[200:203], v[86:89]
	v_mfma_f32_16x16x32_bf16 v[82:85], v[176:179], v[200:203], v[82:85]
	v_mfma_f32_16x16x32_bf16 v[70:73], v[168:171], v[208:211], v[70:73]
	v_mfma_f32_16x16x32_bf16 v[66:69], v[176:179], v[208:211], v[66:69]
	s_setprio 0
	s_barrier
; #define PG8_STAGE(bufoff, gbase, voff) do { _Pragma("unroll") for (int _i = 0; _i < 2; ++_i) \
;         __builtin_amdgcn_global_load_lds((const unsigned*)((const char*)(gbase) + (voff)[_i]), (PG8_LAS unsigned*)(lds + (bufoff) + ldsw + _i * 8192), 16, 0, 0); } while (0)
; #define PG8_LDA(dst, b, h) do { _Pragma("unroll") for (int m = 0; m < 4; ++m) _Pragma("unroll") for (int k = 0; k < 2; ++k) dst[m][k] = *(const PG8_LAS bf16x8*)(lds + PG8_SA(b, h) + aoff + m * 2048 + k * 1024); } while (0)
; #define PG8_MMA(ai, bj, At, Bt) do { __builtin_amdgcn_s_setprio(1); _Pragma("unroll") for (int m = 0; m < 4; ++m) _Pragma("unroll") for (int n = 0; n < 2; ++n) _Pragma("unroll") for (int k = 0; k < 2; ++k) \
;         acc[ai][bj][m][n] = __builtin_amdgcn_mfma_f32_16x16x32_bf16(Bt[n][k], At[m][k], acc[ai][bj][m][n], 0, 0, 0); __builtin_amdgcn_s_setprio(0); } while (0)
; #define PG8_WAIT_V(n) asm volatile("s_waitcnt vmcnt(" #n ")" ::: "memory")
; #define PG8_WAIT_L(n) asm volatile("s_waitcnt lgkmcnt(" #n ")" ::: "memory")
; #define PG8_BAR __builtin_amdgcn_s_barrier()
; #define PG8_SCHED __builtin_amdgcn_sched_barrier(0)
; template <class Epi, class Sched, bool ALIGN_EPI = false, bool SP2 = false>
; __device__ __forceinline__ void gemm_phase(PG8_LAS unsigned char* lds, const Gemm g, const Sched& S, const Epi& E) {
;     ...
;             PG8_LDA(At, 1, 1); PG8_STAGE(PG8_SB(1, 0), b3, voffB); PG8_STAGE(PG8_SB(1, 1), b3 + hstep, voffB); PG8_STAGE(PG8_SA(1, 0), a3, voffA);
;             PG8_WAIT_V(8); PG8_WAIT_L(0); PG8_BAR; PG8_MMA(1, 0, At, B0); PG8_MMA(1, 1, At, B1); PG8_BAR; PG8_SCHED;
	s_add_i32 s24, s26, s30
	v_lshl_add_u64 v[222:223], v[232:233], 0, s[64:65]
	s_mov_b32 m0, s24
	ds_read_b128 v[180:183], v247 offset:49152
	ds_read_b128 v[184:187], v247 offset:50176
	ds_read_b128 v[188:191], v247 offset:51200
	ds_read_b128 v[192:195], v247 offset:52224
	ds_read_b128 v[196:199], v247 offset:53248
	ds_read_b128 v[200:203], v247 offset:54272
	ds_read_b128 v[204:207], v247 offset:55296
	ds_read_b128 v[208:211], v247 offset:56320
	global_load_lds_dwordx4 v[222:223], off
	s_add_i32 m0, s24, 0x2000
	s_add_u32 s22, s22, 0x80080
	v_lshl_add_u64 v[222:223], v[248:249], 0, s[64:65]
	s_addc_u32 s23, s23, 0
	s_add_i32 s24, s27, s30
	global_load_lds_dwordx4 v[222:223], off
	v_lshl_add_u64 v[222:223], s[22:23], 0, v[0:1]
	s_mov_b32 m0, s24
	v_lshl_add_u64 v[220:221], v[220:221], 0, s[64:65]
	global_load_lds_dwordx4 v[222:223], off
	v_lshl_add_u64 v[222:223], s[22:23], 0, v[126:127]
	s_add_i32 m0, s24, 0x2000
	s_nop 0
	global_load_lds_dwordx4 v[222:223], off
	v_lshl_add_u64 v[222:223], v[250:251], 0, s[64:65]
	s_mov_b32 m0, s37
	s_nop 0
	global_load_lds_dwordx4 v[222:223], off
	s_mov_b32 m0, s84
	s_nop 0
	global_load_lds_dwordx4 v[220:221], off
	s_waitcnt vmcnt(8) lgkmcnt(0)
	s_setprio 1
	s_barrier
	v_mfma_f32_16x16x32_bf16 v[62:65], v[148:151], v[180:183], v[62:65]
	v_mfma_f32_16x16x32_bf16 v[58:61], v[156:159], v[180:183], v[58:61]
	v_mfma_f32_16x16x32_bf16 v[46:49], v[148:151], v[188:191], v[46:49]
	v_mfma_f32_16x16x32_bf16 v[42:45], v[156:159], v[188:191], v[42:45]
	v_mfma_f32_16x16x32_bf16 v[30:33], v[148:151], v[196:199], v[30:33]
	v_mfma_f32_16x16x32_bf16 v[26:29], v[156:159], v[196:199], v[26:29]
	v_mfma_f32_16x16x32_bf16 v[14:17], v[148:151], v[204:207], v[14:17]
	v_mfma_f32_16x16x32_bf16 v[10:13], v[156:159], v[204:207], v[10:13]
	v_mfma_f32_16x16x32_bf16 v[62:65], v[152:155], v[184:187], v[62:65]
	v_mfma_f32_16x16x32_bf16 v[58:61], v[160:163], v[184:187], v[58:61]
	v_mfma_f32_16x16x32_bf16 v[46:49], v[152:155], v[192:195], v[46:49]
	v_mfma_f32_16x16x32_bf16 v[42:45], v[160:163], v[192:195], v[42:45]
	v_mfma_f32_16x16x32_bf16 v[30:33], v[152:155], v[200:203], v[30:33]
	v_mfma_f32_16x16x32_bf16 v[26:29], v[160:163], v[200:203], v[26:29]
	v_mfma_f32_16x16x32_bf16 v[14:17], v[152:155], v[208:211], v[14:17]
	v_mfma_f32_16x16x32_bf16 v[10:13], v[160:163], v[208:211], v[10:13]
	v_mfma_f32_16x16x32_bf16 v[54:57], v[164:167], v[180:183], v[54:57]
	v_mfma_f32_16x16x32_bf16 v[50:53], v[172:175], v[180:183], v[50:53]
	v_mfma_f32_16x16x32_bf16 v[38:41], v[164:167], v[188:191], v[38:41]
	v_mfma_f32_16x16x32_bf16 v[34:37], v[172:175], v[188:191], v[34:37]
	v_mfma_f32_16x16x32_bf16 v[22:25], v[164:167], v[196:199], v[22:25]
	v_mfma_f32_16x16x32_bf16 v[18:21], v[172:175], v[196:199], v[18:21]
	v_mfma_f32_16x16x32_bf16 v[6:9], v[164:167], v[204:207], v[6:9]
	v_mfma_f32_16x16x32_bf16 v[2:5], v[172:175], v[204:207], v[2:5]
	v_mfma_f32_16x16x32_bf16 v[54:57], v[168:171], v[184:187], v[54:57]
	v_mfma_f32_16x16x32_bf16 v[50:53], v[176:179], v[184:187], v[50:53]
	v_mfma_f32_16x16x32_bf16 v[38:41], v[168:171], v[192:195], v[38:41]
	v_mfma_f32_16x16x32_bf16 v[34:37], v[176:179], v[192:195], v[34:37]
	v_mfma_f32_16x16x32_bf16 v[22:25], v[168:171], v[200:203], v[22:25]
	v_mfma_f32_16x16x32_bf16 v[18:21], v[176:179], v[200:203], v[18:21]
	v_mfma_f32_16x16x32_bf16 v[6:9], v[168:171], v[208:211], v[6:9]
	v_mfma_f32_16x16x32_bf16 v[2:5], v[176:179], v[208:211], v[2:5]
	s_setprio 0
	s_barrier
	s_add_i32 s22, s76, 2
	s_add_u32 s20, s20, 0x100
	s_addc_u32 s21, s21, 0
	s_cmp_gt_u32 s76, 29
	s_mov_b32 s76, s22
	s_cbranch_scc1 .LBB0_742

;     __device__ __forceinline__ bool next(int i, Unit& u) const { if (i > 0 || c < first) return false; const int idx = c - first; u.pm = idx % nM; u.pn = idx / nM; return true; }
; #define PG8_STAGE(bufoff, gbase, voff) do { _Pragma("unroll") for (int _i = 0; _i < 2; ++_i) \
;         __builtin_amdgcn_global_load_lds((const unsigned*)((const char*)(gbase) + (voff)[_i]), (PG8_LAS unsigned*)(lds + (bufoff) + ldsw + _i * 8192), 16, 0, 0); } while (0)
; #define PG8_LDA(dst, b, h) do { _Pragma("unroll") for (int m = 0; m < 4; ++m) _Pragma("unroll") for (int k = 0; k < 2; ++k) dst[m][k] = *(const PG8_LAS bf16x8*)(lds + PG8_SA(b, h) + aoff + m * 2048 + k * 1024); } while (0)
; #define PG8_WAIT_V(n) asm volatile("s_waitcnt vmcnt(" #n ")" ::: "memory")
; #define PG8_WAIT_L(n) asm volatile("s_waitcnt lgkmcnt(" #n ")" ::: "memory")
; #define PG8_BAR __builtin_amdgcn_s_barrier()
; template <class Epi, class Sched, bool ALIGN_EPI = false, bool SP2 = false>
; __device__ __forceinline__ void gemm_phase(PG8_LAS unsigned char* lds, const Gemm g, const Sched& S, const Epi& E) {
;     ...
;         const bool has_next = S.next(ui + 1, nxt);
;         const char* nA = has_next ? (const char*)g.A + (size_t)nxt.pm * tstep : cA; const char* nB = has_next ? (const char*)g.Bt + (size_t)nxt.pn * tstep : cB;
;         for (int t = 0; t < nt; t += 2) {
;             if constexpr (Epi::HAS_MID) { if (t == Epi::MID0 || t == Epi::MID1) E.mid(acc, cur, wr, wc, fr, fq, t == Epi::MID0 ? 0 : 1); }
;             const bool last = (t == nt - 2);
;             const char* a1 = cA + (size_t)(t + 1) * kstep;
;             const char* a2 = last ? nA : cA + (size_t)(t + 2) * kstep; const char* b2 = last ? nB : cB + (size_t)(t + 2) * kstep;
;             const char* a3 = a2 + kstep; const char* b3 = b2 + kstep;
;             if (last && has_next) S.a_ready(nxt);
;             if constexpr (SP2) {
;             PG8_LDB(B0, 0, 0); PG8_LDB(B1, 0, 1); PG8_SCHED; PG8_LDA(At, 0, 0); PG8_STAGE(PG8_SA(1, 1), a1 + hstep, voffA);
;             PG8_WAIT_V(8); PG8_WAIT_L(0); PG8_BAR; PG8_MMA(0, 0, At, B0); PG8_MMA(0, 1, At, B1); PG8_BAR; PG8_SCHED;
;             PG8_LDA(At, 0, 1); PG8_STAGE(PG8_SB(0, 0), b2, voffB); PG8_STAGE(PG8_SB(0, 1), b2 + hstep, voffB); PG8_STAGE(PG8_SA(0, 0), a2, voffA);
;             PG8_WAIT_V(8); PG8_WAIT_L(0); PG8_BAR; PG8_MMA(1, 0, At, B0); PG8_MMA(1, 1, At, B1); PG8_BAR; PG8_SCHED;
.LBB0_808:
	s_add_u32 s28, s8, 0xfff80080
	s_addc_u32 s29, s9, -1
	s_add_i32 s48, 0, 0x10000
	s_cmp_eq_u32 s87, 28
	s_cselect_b32 s31, s23, s29
	s_cselect_b32 s30, s67, s28
	v_add_u32_e32 v160, s48, v163
	s_cselect_b32 s29, s21, s86
	s_cselect_b32 s28, s81, s83
	s_add_i32 s91, 0, 0x14000
	ds_read_b128 v[152:155], v160
	ds_read_b128 v[156:159], v160 offset:1024
	ds_read_b128 v[166:169], v160 offset:2048
	ds_read_b128 v[170:173], v160 offset:3072
	v_add_u32_e32 v160, s91, v163
	ds_read_b128 v[174:177], v160
	ds_read_b128 v[178:181], v160 offset:1024
	ds_read_b128 v[182:185], v160 offset:2048
	ds_read_b128 v[186:189], v160 offset:3072
	v_lshl_add_u64 v[160:161], s[8:9], 0, v[148:149]
	s_add_i32 m0, s13, 0xc000
	ds_read_b128 v[190:193], v165
	ds_read_b128 v[194:197], v165 offset:1024
	ds_read_b128 v[198:201], v165 offset:2048
	ds_read_b128 v[202:205], v165 offset:3072
	ds_read_b128 v[206:209], v165 offset:4096
	ds_read_b128 v[210:213], v165 offset:5120
	ds_read_b128 v[214:217], v165 offset:6144
	ds_read_b128 v[224:227], v165 offset:7168
	global_load_lds_dwordx4 v[160:161], off
	v_lshl_add_u64 v[160:161], s[8:9], 0, v[150:151]
	s_add_i32 m0, s13, 0xe000
	s_nop 0
	global_load_lds_dwordx4 v[160:161], off
	s_waitcnt vmcnt(8) lgkmcnt(0)
	s_setprio 1
	s_barrier
	v_mfma_f32_16x16x32_bf16 v[144:147], v[152:155], v[190:193], v[144:147]
	v_mfma_f32_16x16x32_bf16 v[122:125], v[166:169], v[190:193], v[122:125]
	v_mfma_f32_16x16x32_bf16 v[110:113], v[152:155], v[198:201], v[110:113]
	v_mfma_f32_16x16x32_bf16 v[106:109], v[166:169], v[198:201], v[106:109]
	v_mfma_f32_16x16x32_bf16 v[94:97], v[152:155], v[206:209], v[94:97]
	v_mfma_f32_16x16x32_bf16 v[90:93], v[166:169], v[206:209], v[90:93]
	v_mfma_f32_16x16x32_bf16 v[78:81], v[152:155], v[214:217], v[78:81]
	v_mfma_f32_16x16x32_bf16 v[74:77], v[166:169], v[214:217], v[74:77]
	v_mfma_f32_16x16x32_bf16 v[144:147], v[156:159], v[194:197], v[144:147]
	v_mfma_f32_16x16x32_bf16 v[122:125], v[170:173], v[194:197], v[122:125]
	v_mfma_f32_16x16x32_bf16 v[110:113], v[156:159], v[202:205], v[110:113]
	v_mfma_f32_16x16x32_bf16 v[106:109], v[170:173], v[202:205], v[106:109]
	v_mfma_f32_16x16x32_bf16 v[94:97], v[156:159], v[210:213], v[94:97]
	v_mfma_f32_16x16x32_bf16 v[90:93], v[170:173], v[210:213], v[90:93]
	v_mfma_f32_16x16x32_bf16 v[78:81], v[156:159], v[224:227], v[78:81]
	v_mfma_f32_16x16x32_bf16 v[74:77], v[170:173], v[224:227], v[74:77]
	v_mfma_f32_16x16x32_bf16 v[118:121], v[174:177], v[190:193], v[118:121]
	v_mfma_f32_16x16x32_bf16 v[114:117], v[182:185], v[190:193], v[114:117]
	v_mfma_f32_16x16x32_bf16 v[102:105], v[174:177], v[198:201], v[102:105]
	v_mfma_f32_16x16x32_bf16 v[98:101], v[182:185], v[198:201], v[98:101]
	v_mfma_f32_16x16x32_bf16 v[86:89], v[174:177], v[206:209], v[86:89]
	v_mfma_f32_16x16x32_bf16 v[82:85], v[182:185], v[206:209], v[82:85]
	v_mfma_f32_16x16x32_bf16 v[70:73], v[174:177], v[214:217], v[70:73]
	v_mfma_f32_16x16x32_bf16 v[66:69], v[182:185], v[214:217], v[66:69]
	v_mfma_f32_16x16x32_bf16 v[118:121], v[178:181], v[194:197], v[118:121]
	v_mfma_f32_16x16x32_bf16 v[114:117], v[186:189], v[194:197], v[114:117]
	v_mfma_f32_16x16x32_bf16 v[102:105], v[178:181], v[202:205], v[102:105]
	v_mfma_f32_16x16x32_bf16 v[98:101], v[186:189], v[202:205], v[98:101]
	v_mfma_f32_16x16x32_bf16 v[86:89], v[178:181], v[210:213], v[86:89]
	v_mfma_f32_16x16x32_bf16 v[82:85], v[186:189], v[210:213], v[82:85]
	v_mfma_f32_16x16x32_bf16 v[70:73], v[178:181], v[224:227], v[70:73]
	v_mfma_f32_16x16x32_bf16 v[66:69], v[186:189], v[224:227], v[66:69]
	s_setprio 0
	s_barrier
	s_add_i32 s48, s48, s12
	v_lshl_add_u64 v[160:161], s[28:29], 0, v[0:1]
	s_mov_b32 m0, s48
	ds_read_b128 v[190:193], v165 offset:16384
	ds_read_b128 v[194:197], v165 offset:17408
	ds_read_b128 v[198:201], v165 offset:18432
	ds_read_b128 v[202:205], v165 offset:19456
	ds_read_b128 v[206:209], v165 offset:20480
	ds_read_b128 v[210:213], v165 offset:21504
	ds_read_b128 v[214:217], v165 offset:22528
	ds_read_b128 v[224:227], v165 offset:23552
	global_load_lds_dwordx4 v[160:161], off
	s_add_i32 m0, s48, 0x2000
	s_add_u32 vcc_lo, s28, 0x80000
	v_lshl_add_u64 v[218:219], s[28:29], 0, v[126:127]
	s_addc_u32 vcc_hi, s29, 0
	s_add_i32 s48, s91, s12
	global_load_lds_dwordx4 v[218:219], off
	v_lshl_add_u64 v[220:221], vcc, 0, v[0:1]
	s_mov_b32 m0, s48
	v_lshl_add_u64 v[222:223], s[30:31], 0, v[126:127]
	global_load_lds_dwordx4 v[220:221], off
	v_lshl_add_u64 v[220:221], vcc, 0, v[126:127]
	s_add_i32 m0, s48, 0x2000
	s_nop 0
	global_load_lds_dwordx4 v[220:221], off
	v_lshl_add_u64 v[220:221], s[30:31], 0, v[0:1]
	s_mov_b32 m0, s13
	s_nop 0
	global_load_lds_dwordx4 v[220:221], off
	s_mov_b32 m0, s34
	s_nop 0
	global_load_lds_dwordx4 v[222:223], off
	s_waitcnt vmcnt(8) lgkmcnt(0)
	s_setprio 1
	s_barrier
; #define PG8_STAGE(bufoff, gbase, voff) do { _Pragma("unroll") for (int _i = 0; _i < 2; ++_i) \
;         __builtin_amdgcn_global_load_lds((const unsigned*)((const char*)(gbase) + (voff)[_i]), (PG8_LAS unsigned*)(lds + (bufoff) + ldsw + _i * 8192), 16, 0, 0); } while (0)
; #define PG8_LDA(dst, b, h) do { _Pragma("unroll") for (int m = 0; m < 4; ++m) _Pragma("unroll") for (int k = 0; k < 2; ++k) dst[m][k] = *(const PG8_LAS bf16x8*)(lds + PG8_SA(b, h) + aoff + m * 2048 + k * 1024); } while (0)
; #define PG8_LDB(dst, b, h) do { _Pragma("unroll") for (int n = 0; n < 2; ++n) _Pragma("unroll") for (int k = 0; k < 2; ++k) dst[n][k] = *(const PG8_LAS bf16x8*)(lds + PG8_SB(b, h) + boff + n * 2048 + k * 1024); } while (0)
; #define PG8_MMA(ai, bj, At, Bt) do { __builtin_amdgcn_s_setprio(1); _Pragma("unroll") for (int m = 0; m < 4; ++m) _Pragma("unroll") for (int n = 0; n < 2; ++n) _Pragma("unroll") for (int k = 0; k < 2; ++k) \
;         acc[ai][bj][m][n] = __builtin_amdgcn_mfma_f32_16x16x32_bf16(Bt[n][k], At[m][k], acc[ai][bj][m][n], 0, 0, 0); __builtin_amdgcn_s_setprio(0); } while (0)
; #define PG8_WAIT_V(n) asm volatile("s_waitcnt vmcnt(" #n ")" ::: "memory")
; #define PG8_WAIT_L(n) asm volatile("s_waitcnt lgkmcnt(" #n ")" ::: "memory")
; #define PG8_BAR __builtin_amdgcn_s_barrier()
; #define PG8_SCHED __builtin_amdgcn_sched_barrier(0)
; template <class Epi, class Sched, bool ALIGN_EPI = false, bool SP2 = false>
; __device__ __forceinline__ void gemm_phase(PG8_LAS unsigned char* lds, const Gemm g, const Sched& S, const Epi& E) {
;     ...
;             PG8_WAIT_V(8); PG8_WAIT_L(0); PG8_BAR; PG8_MMA(1, 0, At, B0); PG8_MMA(1, 1, At, B1); PG8_BAR; PG8_SCHED;
;             PG8_LDB(B0, 1, 0); PG8_LDB(B1, 1, 1); PG8_SCHED; PG8_LDA(At, 1, 0); PG8_STAGE(PG8_SA(0, 1), a2 + hstep, voffA);
;             PG8_WAIT_V(8); PG8_WAIT_L(0); PG8_BAR; PG8_MMA(0, 0, At, B0); PG8_MMA(0, 1, At, B1); PG8_BAR; PG8_SCHED;
	v_mfma_f32_16x16x32_bf16 v[62:65], v[152:155], v[190:193], v[62:65]
	v_mfma_f32_16x16x32_bf16 v[58:61], v[166:169], v[190:193], v[58:61]
	v_mfma_f32_16x16x32_bf16 v[46:49], v[152:155], v[198:201], v[46:49]
	v_mfma_f32_16x16x32_bf16 v[42:45], v[166:169], v[198:201], v[42:45]
	v_mfma_f32_16x16x32_bf16 v[30:33], v[152:155], v[206:209], v[30:33]
	v_mfma_f32_16x16x32_bf16 v[26:29], v[166:169], v[206:209], v[26:29]
	v_mfma_f32_16x16x32_bf16 v[14:17], v[152:155], v[214:217], v[14:17]
	v_mfma_f32_16x16x32_bf16 v[10:13], v[166:169], v[214:217], v[10:13]
	v_mfma_f32_16x16x32_bf16 v[62:65], v[156:159], v[194:197], v[62:65]
	v_mfma_f32_16x16x32_bf16 v[58:61], v[170:173], v[194:197], v[58:61]
	v_mfma_f32_16x16x32_bf16 v[46:49], v[156:159], v[202:205], v[46:49]
	v_mfma_f32_16x16x32_bf16 v[42:45], v[170:173], v[202:205], v[42:45]
	v_mfma_f32_16x16x32_bf16 v[30:33], v[156:159], v[210:213], v[30:33]
	v_mfma_f32_16x16x32_bf16 v[26:29], v[170:173], v[210:213], v[26:29]
	v_mfma_f32_16x16x32_bf16 v[14:17], v[156:159], v[224:227], v[14:17]
	v_mfma_f32_16x16x32_bf16 v[10:13], v[170:173], v[224:227], v[10:13]
	v_mfma_f32_16x16x32_bf16 v[54:57], v[174:177], v[190:193], v[54:57]
	v_mfma_f32_16x16x32_bf16 v[50:53], v[182:185], v[190:193], v[50:53]
	v_mfma_f32_16x16x32_bf16 v[38:41], v[174:177], v[198:201], v[38:41]
	v_mfma_f32_16x16x32_bf16 v[34:37], v[182:185], v[198:201], v[34:37]
	v_mfma_f32_16x16x32_bf16 v[22:25], v[174:177], v[206:209], v[22:25]
	v_mfma_f32_16x16x32_bf16 v[18:21], v[182:185], v[206:209], v[18:21]
	v_mfma_f32_16x16x32_bf16 v[6:9], v[174:177], v[214:217], v[6:9]
	v_mfma_f32_16x16x32_bf16 v[2:5], v[182:185], v[214:217], v[2:5]
	v_mfma_f32_16x16x32_bf16 v[54:57], v[178:181], v[194:197], v[54:57]
	v_mfma_f32_16x16x32_bf16 v[50:53], v[186:189], v[194:197], v[50:53]
	v_mfma_f32_16x16x32_bf16 v[38:41], v[178:181], v[202:205], v[38:41]
	v_mfma_f32_16x16x32_bf16 v[34:37], v[186:189], v[202:205], v[34:37]
	v_mfma_f32_16x16x32_bf16 v[22:25], v[178:181], v[210:213], v[22:25]
	v_mfma_f32_16x16x32_bf16 v[18:21], v[186:189], v[210:213], v[18:21]
	v_mfma_f32_16x16x32_bf16 v[6:9], v[178:181], v[224:227], v[6:9]
	v_mfma_f32_16x16x32_bf16 v[2:5], v[186:189], v[224:227], v[2:5]
	s_setprio 0
	s_barrier
	s_add_i32 s48, 0, 0x18000
	s_add_i32 s91, 0, 0x1c000
	v_add_u32_e32 v170, s48, v163
	v_add_u32_e32 v186, s91, v163
	ds_read_b128 v[152:155], v170
	ds_read_b128 v[156:159], v170 offset:1024
	ds_read_b128 v[166:169], v170 offset:2048
	ds_read_b128 v[170:173], v170 offset:3072
	ds_read_b128 v[174:177], v186
	ds_read_b128 v[178:181], v186 offset:1024
	ds_read_b128 v[182:185], v186 offset:2048
	ds_read_b128 v[186:189], v186 offset:3072
	s_add_u32 s30, s30, 0x80000
	s_addc_u32 s31, s31, 0
	s_mov_b32 m0, s35
	v_lshl_add_u64 v[228:229], s[30:31], 0, v[0:1]
	ds_read_b128 v[190:193], v165 offset:32768
	ds_read_b128 v[194:197], v165 offset:33792
	ds_read_b128 v[198:201], v165 offset:34816
	ds_read_b128 v[202:205], v165 offset:35840
	ds_read_b128 v[206:209], v165 offset:36864
	ds_read_b128 v[210:213], v165 offset:37888
	ds_read_b128 v[214:217], v165 offset:38912
	ds_read_b128 v[224:227], v165 offset:39936
	global_load_lds_dwordx4 v[228:229], off
	v_lshl_add_u64 v[228:229], s[30:31], 0, v[126:127]
	s_mov_b32 m0, s42
	s_nop 0
	global_load_lds_dwordx4 v[228:229], off
	s_waitcnt vmcnt(8) lgkmcnt(0)
	s_setprio 1
	s_barrier
	v_mfma_f32_16x16x32_bf16 v[144:147], v[152:155], v[190:193], v[144:147]
	v_mfma_f32_16x16x32_bf16 v[122:125], v[166:169], v[190:193], v[122:125]
	v_mfma_f32_16x16x32_bf16 v[110:113], v[152:155], v[198:201], v[110:113]
	v_mfma_f32_16x16x32_bf16 v[106:109], v[166:169], v[198:201], v[106:109]
	v_mfma_f32_16x16x32_bf16 v[94:97], v[152:155], v[206:209], v[94:97]
	v_mfma_f32_16x16x32_bf16 v[90:93], v[166:169], v[206:209], v[90:93]
	v_mfma_f32_16x16x32_bf16 v[78:81], v[152:155], v[214:217], v[78:81]
	v_mfma_f32_16x16x32_bf16 v[74:77], v[166:169], v[214:217], v[74:77]
	v_mfma_f32_16x16x32_bf16 v[144:147], v[156:159], v[194:197], v[144:147]
	v_mfma_f32_16x16x32_bf16 v[122:125], v[170:173], v[194:197], v[122:125]
	v_mfma_f32_16x16x32_bf16 v[110:113], v[156:159], v[202:205], v[110:113]
	v_mfma_f32_16x16x32_bf16 v[106:109], v[170:173], v[202:205], v[106:109]
	v_mfma_f32_16x16x32_bf16 v[94:97], v[156:159], v[210:213], v[94:97]
	v_mfma_f32_16x16x32_bf16 v[90:93], v[170:173], v[210:213], v[90:93]
	v_mfma_f32_16x16x32_bf16 v[78:81], v[156:159], v[224:227], v[78:81]
	v_mfma_f32_16x16x32_bf16 v[74:77], v[170:173], v[224:227], v[74:77]
	v_mfma_f32_16x16x32_bf16 v[118:121], v[174:177], v[190:193], v[118:121]
	v_mfma_f32_16x16x32_bf16 v[114:117], v[182:185], v[190:193], v[114:117]
	v_mfma_f32_16x16x32_bf16 v[102:105], v[174:177], v[198:201], v[102:105]
	v_mfma_f32_16x16x32_bf16 v[98:101], v[182:185], v[198:201], v[98:101]
	v_mfma_f32_16x16x32_bf16 v[86:89], v[174:177], v[206:209], v[86:89]
	v_mfma_f32_16x16x32_bf16 v[82:85], v[182:185], v[206:209], v[82:85]
	v_mfma_f32_16x16x32_bf16 v[70:73], v[174:177], v[214:217], v[70:73]
	v_mfma_f32_16x16x32_bf16 v[66:69], v[182:185], v[214:217], v[66:69]
	v_mfma_f32_16x16x32_bf16 v[118:121], v[178:181], v[194:197], v[118:121]
	v_mfma_f32_16x16x32_bf16 v[114:117], v[186:189], v[194:197], v[114:117]
	v_mfma_f32_16x16x32_bf16 v[102:105], v[178:181], v[202:205], v[102:105]
	v_mfma_f32_16x16x32_bf16 v[98:101], v[186:189], v[202:205], v[98:101]
	v_mfma_f32_16x16x32_bf16 v[86:89], v[178:181], v[210:213], v[86:89]
	v_mfma_f32_16x16x32_bf16 v[82:85], v[186:189], v[210:213], v[82:85]
	v_mfma_f32_16x16x32_bf16 v[70:73], v[178:181], v[224:227], v[70:73]
	v_mfma_f32_16x16x32_bf16 v[66:69], v[186:189], v[224:227], v[66:69]
	s_setprio 0
	s_barrier
; #define PG8_STAGE(bufoff, gbase, voff) do { _Pragma("unroll") for (int _i = 0; _i < 2; ++_i) \
;         __builtin_amdgcn_global_load_lds((const unsigned*)((const char*)(gbase) + (voff)[_i]), (PG8_LAS unsigned*)(lds + (bufoff) + ldsw + _i * 8192), 16, 0, 0); } while (0)
; #define PG8_LDA(dst, b, h) do { _Pragma("unroll") for (int m = 0; m < 4; ++m) _Pragma("unroll") for (int k = 0; k < 2; ++k) dst[m][k] = *(const PG8_LAS bf16x8*)(lds + PG8_SA(b, h) + aoff + m * 2048 + k * 1024); } while (0)
; #define PG8_MMA(ai, bj, At, Bt) do { __builtin_amdgcn_s_setprio(1); _Pragma("unroll") for (int m = 0; m < 4; ++m) _Pragma("unroll") for (int n = 0; n < 2; ++n) _Pragma("unroll") for (int k = 0; k < 2; ++k) \
;         acc[ai][bj][m][n] = __builtin_amdgcn_mfma_f32_16x16x32_bf16(Bt[n][k], At[m][k], acc[ai][bj][m][n], 0, 0, 0); __builtin_amdgcn_s_setprio(0); } while (0)
; #define PG8_WAIT_V(n) asm volatile("s_waitcnt vmcnt(" #n ")" ::: "memory")
; #define PG8_WAIT_L(n) asm volatile("s_waitcnt lgkmcnt(" #n ")" ::: "memory")
; #define PG8_BAR __builtin_amdgcn_s_barrier()
; #define PG8_SCHED __builtin_amdgcn_sched_barrier(0)
; template <class Epi, class Sched, bool ALIGN_EPI = false, bool SP2 = false>
; __device__ __forceinline__ void gemm_phase(PG8_LAS unsigned char* lds, const Gemm g, const Sched& S, const Epi& E) {
;     ...
;             PG8_LDA(At, 1, 1); PG8_STAGE(PG8_SB(1, 0), b3, voffB); PG8_STAGE(PG8_SB(1, 1), b3 + hstep, voffB); PG8_STAGE(PG8_SA(1, 0), a3, voffA);
;             PG8_WAIT_V(8); PG8_WAIT_L(0); PG8_BAR; PG8_MMA(1, 0, At, B0); PG8_MMA(1, 1, At, B1); PG8_BAR; PG8_SCHED;
;     ...
;         if constexpr (ALIGN_EPI) { if (wr == 0) PG8_BAR; }
	s_add_i32 s30, s48, s12
	v_lshl_add_u64 v[160:161], v[160:161], 0, s[64:65]
	s_mov_b32 m0, s30
	ds_read_b128 v[190:193], v165 offset:49152
	ds_read_b128 v[194:197], v165 offset:50176
	ds_read_b128 v[198:201], v165 offset:51200
	ds_read_b128 v[202:205], v165 offset:52224
	ds_read_b128 v[206:209], v165 offset:53248
	ds_read_b128 v[210:213], v165 offset:54272
	ds_read_b128 v[214:217], v165 offset:55296
	ds_read_b128 v[224:227], v165 offset:56320
	global_load_lds_dwordx4 v[160:161], off
	s_add_i32 m0, s30, 0x2000
	s_add_u32 s28, s28, 0x80080
	v_lshl_add_u64 v[160:161], v[218:219], 0, s[64:65]
	s_addc_u32 s29, s29, 0
	s_add_i32 s30, s91, s12
	global_load_lds_dwordx4 v[160:161], off
	v_lshl_add_u64 v[160:161], s[28:29], 0, v[0:1]
	s_mov_b32 m0, s30
	s_nop 0
	global_load_lds_dwordx4 v[160:161], off
	v_lshl_add_u64 v[160:161], s[28:29], 0, v[126:127]
	s_add_i32 m0, s30, 0x2000
	s_nop 0
	global_load_lds_dwordx4 v[160:161], off
	v_lshl_add_u64 v[160:161], v[220:221], 0, s[64:65]
	s_mov_b32 m0, s43
	s_nop 0
	global_load_lds_dwordx4 v[160:161], off
	v_lshl_add_u64 v[160:161], v[222:223], 0, s[64:65]
	s_mov_b32 m0, s76
	s_nop 0
	global_load_lds_dwordx4 v[160:161], off
	s_waitcnt vmcnt(8) lgkmcnt(0)
	s_setprio 1
	s_barrier
	v_mfma_f32_16x16x32_bf16 v[62:65], v[152:155], v[190:193], v[62:65]
	v_mfma_f32_16x16x32_bf16 v[58:61], v[166:169], v[190:193], v[58:61]
	v_mfma_f32_16x16x32_bf16 v[46:49], v[152:155], v[198:201], v[46:49]
	v_mfma_f32_16x16x32_bf16 v[42:45], v[166:169], v[198:201], v[42:45]
	v_mfma_f32_16x16x32_bf16 v[30:33], v[152:155], v[206:209], v[30:33]
	v_mfma_f32_16x16x32_bf16 v[26:29], v[166:169], v[206:209], v[26:29]
	v_mfma_f32_16x16x32_bf16 v[14:17], v[152:155], v[214:217], v[14:17]
	v_mfma_f32_16x16x32_bf16 v[10:13], v[166:169], v[214:217], v[10:13]
	v_mfma_f32_16x16x32_bf16 v[62:65], v[156:159], v[194:197], v[62:65]
	v_mfma_f32_16x16x32_bf16 v[58:61], v[170:173], v[194:197], v[58:61]
	v_mfma_f32_16x16x32_bf16 v[46:49], v[156:159], v[202:205], v[46:49]
	v_mfma_f32_16x16x32_bf16 v[42:45], v[170:173], v[202:205], v[42:45]
	v_mfma_f32_16x16x32_bf16 v[30:33], v[156:159], v[210:213], v[30:33]
	v_mfma_f32_16x16x32_bf16 v[26:29], v[170:173], v[210:213], v[26:29]
	v_mfma_f32_16x16x32_bf16 v[14:17], v[156:159], v[224:227], v[14:17]
	v_mfma_f32_16x16x32_bf16 v[10:13], v[170:173], v[224:227], v[10:13]
	v_mfma_f32_16x16x32_bf16 v[54:57], v[174:177], v[190:193], v[54:57]
	v_mfma_f32_16x16x32_bf16 v[50:53], v[182:185], v[190:193], v[50:53]
	v_mfma_f32_16x16x32_bf16 v[38:41], v[174:177], v[198:201], v[38:41]
	v_mfma_f32_16x16x32_bf16 v[34:37], v[182:185], v[198:201], v[34:37]
	v_mfma_f32_16x16x32_bf16 v[22:25], v[174:177], v[206:209], v[22:25]
	v_mfma_f32_16x16x32_bf16 v[18:21], v[182:185], v[206:209], v[18:21]
	v_mfma_f32_16x16x32_bf16 v[6:9], v[174:177], v[214:217], v[6:9]
	v_mfma_f32_16x16x32_bf16 v[2:5], v[182:185], v[214:217], v[2:5]
	v_mfma_f32_16x16x32_bf16 v[54:57], v[178:181], v[194:197], v[54:57]
	v_mfma_f32_16x16x32_bf16 v[50:53], v[186:189], v[194:197], v[50:53]
	v_mfma_f32_16x16x32_bf16 v[38:41], v[178:181], v[202:205], v[38:41]
	v_mfma_f32_16x16x32_bf16 v[34:37], v[186:189], v[202:205], v[34:37]
	v_mfma_f32_16x16x32_bf16 v[22:25], v[178:181], v[210:213], v[22:25]
	v_mfma_f32_16x16x32_bf16 v[18:21], v[186:189], v[210:213], v[18:21]
	v_mfma_f32_16x16x32_bf16 v[6:9], v[178:181], v[224:227], v[6:9]
	v_mfma_f32_16x16x32_bf16 v[2:5], v[186:189], v[224:227], v[2:5]
	s_setprio 0
	s_barrier
	s_add_i32 s87, s87, 2
	s_add_u32 s8, s8, 0x100
	s_addc_u32 s9, s9, 0
	s_add_u32 s83, s83, 0x100
	s_addc_u32 s86, s86, 0
	s_cmp_gt_u32 s87, 29
	s_cbranch_scc0 .LBB0_808
	s_and_b64 vcc, exec, s[18:19]
	s_cbranch_vccz .LBB0_811
	s_barrier

; #define PG8_STAGE(bufoff, gbase, voff) do { _Pragma("unroll") for (int _i = 0; _i < 2; ++_i) \
;         __builtin_amdgcn_global_load_lds((const unsigned*)((const char*)(gbase) + (voff)[_i]), (PG8_LAS unsigned*)(lds + (bufoff) + ldsw + _i * 8192), 16, 0, 0); } while (0)
; #define PG8_LDA(dst, b, h) do { _Pragma("unroll") for (int m = 0; m < 4; ++m) _Pragma("unroll") for (int k = 0; k < 2; ++k) dst[m][k] = *(const PG8_LAS bf16x8*)(lds + PG8_SA(b, h) + aoff + m * 2048 + k * 1024); } while (0)
; #define PG8_LDB(dst, b, h) do { _Pragma("unroll") for (int n = 0; n < 2; ++n) _Pragma("unroll") for (int k = 0; k < 2; ++k) dst[n][k] = *(const PG8_LAS bf16x8*)(lds + PG8_SB(b, h) + boff + n * 2048 + k * 1024); } while (0)
; #define PG8_MMA(ai, bj, At, Bt) do { __builtin_amdgcn_s_setprio(1); _Pragma("unroll") for (int m = 0; m < 4; ++m) _Pragma("unroll") for (int n = 0; n < 2; ++n) _Pragma("unroll") for (int k = 0; k < 2; ++k) \
;         acc[ai][bj][m][n] = __builtin_amdgcn_mfma_f32_16x16x32_bf16(Bt[n][k], At[m][k], acc[ai][bj][m][n], 0, 0, 0); __builtin_amdgcn_s_setprio(0); } while (0)
; #define PG8_WAIT_V(n) asm volatile("s_waitcnt vmcnt(" #n ")" ::: "memory")
; #define PG8_WAIT_L(n) asm volatile("s_waitcnt lgkmcnt(" #n ")" ::: "memory")
; template <class Epi, class Sched, bool ALIGN_EPI = false, bool SP2 = false>
; __device__ __forceinline__ void gemm_phase(PG8_LAS unsigned char* lds, const Gemm g, const Sched& S, const Epi& E) {
;     ...
;             const bool last = (t == nt - 2);
;             const char* a1 = cA + (size_t)(t + 1) * kstep;
;             const char* a2 = last ? nA : cA + (size_t)(t + 2) * kstep; const char* b2 = last ? nB : cB + (size_t)(t + 2) * kstep;
;             const char* a3 = a2 + kstep; const char* b3 = b2 + kstep;
;             if (last && has_next) S.a_ready(nxt);
;             if constexpr (SP2) {
;             PG8_LDB(B0, 0, 0); PG8_LDB(B1, 0, 1); PG8_SCHED; PG8_LDA(At, 0, 0); PG8_STAGE(PG8_SA(1, 1), a1 + hstep, voffA);
;             PG8_WAIT_V(8); PG8_WAIT_L(0); PG8_BAR; PG8_MMA(0, 0, At, B0); PG8_MMA(0, 1, At, B1); PG8_BAR; PG8_SCHED;
;             PG8_LDA(At, 0, 1); PG8_STAGE(PG8_SB(0, 0), b2, voffB); PG8_STAGE(PG8_SB(0, 1), b2 + hstep, voffB); PG8_STAGE(PG8_SA(0, 0), a2, voffA);
;             PG8_WAIT_V(8); PG8_WAIT_L(0); PG8_BAR; PG8_MMA(1, 0, At, B0); PG8_MMA(1, 1, At, B1); PG8_BAR; PG8_SCHED;
.LBB0_910:
	s_add_u32 s28, s0, 0xfff80080
	s_addc_u32 s29, s1, -1
	s_add_i32 s48, 0, 0x10000
	s_cmp_eq_u32 s81, 28
	s_cselect_b32 s31, s21, s29
	s_cselect_b32 s30, s35, s28
	s_cselect_b32 s29, s23, s67
	s_cselect_b32 s28, s40, s41
	s_add_i32 s91, 0, 0x14000
	v_add_u32_e32 v164, s48, v179
	v_add_u32_e32 v176, s91, v179
	ds_read_b128 v[152:155], v164
	ds_read_b128 v[156:159], v164 offset:1024
	ds_read_b128 v[160:163], v164 offset:2048
	ds_read_b128 v[164:167], v164 offset:3072
	ds_read_b128 v[168:171], v176
	ds_read_b128 v[172:175], v176 offset:1024
	ds_read_b128 v[182:185], v176 offset:2048
	ds_read_b128 v[186:189], v176 offset:3072
	v_lshl_add_u64 v[176:177], s[0:1], 0, v[148:149]
	s_add_i32 m0, s43, 0xc000
	ds_read_b128 v[190:193], v181
	ds_read_b128 v[194:197], v181 offset:1024
	ds_read_b128 v[198:201], v181 offset:2048
	ds_read_b128 v[202:205], v181 offset:3072
	ds_read_b128 v[206:209], v181 offset:4096
	ds_read_b128 v[210:213], v181 offset:5120
	ds_read_b128 v[214:217], v181 offset:6144
	ds_read_b128 v[224:227], v181 offset:7168
	global_load_lds_dwordx4 v[176:177], off
	v_lshl_add_u64 v[176:177], s[0:1], 0, v[150:151]
	s_add_i32 m0, s43, 0xe000
	s_nop 0
	global_load_lds_dwordx4 v[176:177], off
	s_waitcnt vmcnt(8) lgkmcnt(0)
	s_setprio 1
	s_barrier
	v_mfma_f32_16x16x32_bf16 v[74:77], v[152:155], v[190:193], v[74:77]
	v_mfma_f32_16x16x32_bf16 v[78:81], v[160:163], v[190:193], v[78:81]
	v_mfma_f32_16x16x32_bf16 v[102:105], v[152:155], v[198:201], v[102:105]
	v_mfma_f32_16x16x32_bf16 v[106:109], v[160:163], v[198:201], v[106:109]
	v_mfma_f32_16x16x32_bf16 v[122:125], v[152:155], v[206:209], v[122:125]
	v_mfma_f32_16x16x32_bf16 v[144:147], v[160:163], v[206:209], v[144:147]
	v_mfma_f32_16x16x32_bf16 v[90:93], v[152:155], v[214:217], v[90:93]
	v_mfma_f32_16x16x32_bf16 v[86:89], v[160:163], v[214:217], v[86:89]
	v_mfma_f32_16x16x32_bf16 v[74:77], v[156:159], v[194:197], v[74:77]
	v_mfma_f32_16x16x32_bf16 v[78:81], v[164:167], v[194:197], v[78:81]
	v_mfma_f32_16x16x32_bf16 v[102:105], v[156:159], v[202:205], v[102:105]
	v_mfma_f32_16x16x32_bf16 v[106:109], v[164:167], v[202:205], v[106:109]
	v_mfma_f32_16x16x32_bf16 v[122:125], v[156:159], v[210:213], v[122:125]
	v_mfma_f32_16x16x32_bf16 v[144:147], v[164:167], v[210:213], v[144:147]
	v_mfma_f32_16x16x32_bf16 v[90:93], v[156:159], v[224:227], v[90:93]
	v_mfma_f32_16x16x32_bf16 v[86:89], v[164:167], v[224:227], v[86:89]
	v_mfma_f32_16x16x32_bf16 v[82:85], v[168:171], v[190:193], v[82:85]
	v_mfma_f32_16x16x32_bf16 v[94:97], v[182:185], v[190:193], v[94:97]
	v_mfma_f32_16x16x32_bf16 v[110:113], v[168:171], v[198:201], v[110:113]
	v_mfma_f32_16x16x32_bf16 v[118:121], v[182:185], v[198:201], v[118:121]
	v_mfma_f32_16x16x32_bf16 v[114:117], v[168:171], v[206:209], v[114:117]
	v_mfma_f32_16x16x32_bf16 v[98:101], v[182:185], v[206:209], v[98:101]
	v_mfma_f32_16x16x32_bf16 v[70:73], v[168:171], v[214:217], v[70:73]
	v_mfma_f32_16x16x32_bf16 v[66:69], v[182:185], v[214:217], v[66:69]
	v_mfma_f32_16x16x32_bf16 v[82:85], v[172:175], v[194:197], v[82:85]
	v_mfma_f32_16x16x32_bf16 v[94:97], v[186:189], v[194:197], v[94:97]
	v_mfma_f32_16x16x32_bf16 v[110:113], v[172:175], v[202:205], v[110:113]
	v_mfma_f32_16x16x32_bf16 v[118:121], v[186:189], v[202:205], v[118:121]
	v_mfma_f32_16x16x32_bf16 v[114:117], v[172:175], v[210:213], v[114:117]
	v_mfma_f32_16x16x32_bf16 v[98:101], v[186:189], v[210:213], v[98:101]
	v_mfma_f32_16x16x32_bf16 v[70:73], v[172:175], v[224:227], v[70:73]
	v_mfma_f32_16x16x32_bf16 v[66:69], v[186:189], v[224:227], v[66:69]
	s_setprio 0
	s_barrier
	s_add_i32 s48, s48, s42
	v_lshl_add_u64 v[176:177], s[28:29], 0, v[0:1]
	s_mov_b32 m0, s48
	ds_read_b128 v[190:193], v181 offset:16384
	ds_read_b128 v[194:197], v181 offset:17408
	ds_read_b128 v[198:201], v181 offset:18432
	ds_read_b128 v[202:205], v181 offset:19456
	ds_read_b128 v[206:209], v181 offset:20480
	ds_read_b128 v[210:213], v181 offset:21504
	ds_read_b128 v[214:217], v181 offset:22528
	ds_read_b128 v[224:227], v181 offset:23552
	global_load_lds_dwordx4 v[176:177], off
	s_add_i32 m0, s48, 0x2000
	s_add_u32 vcc_lo, s28, 0x80000
	v_lshl_add_u64 v[218:219], s[28:29], 0, v[126:127]
	s_addc_u32 vcc_hi, s29, 0
	s_add_i32 s48, s91, s42
	global_load_lds_dwordx4 v[218:219], off
	v_lshl_add_u64 v[220:221], vcc, 0, v[0:1]
	s_mov_b32 m0, s48
	v_lshl_add_u64 v[222:223], s[30:31], 0, v[126:127]
	global_load_lds_dwordx4 v[220:221], off
	v_lshl_add_u64 v[220:221], vcc, 0, v[126:127]
	s_add_i32 m0, s48, 0x2000
	s_nop 0
	global_load_lds_dwordx4 v[220:221], off
	v_lshl_add_u64 v[220:221], s[30:31], 0, v[0:1]
	s_mov_b32 m0, s43
	s_nop 0
	global_load_lds_dwordx4 v[220:221], off
	s_mov_b32 m0, s76
	s_nop 0
	global_load_lds_dwordx4 v[222:223], off
	s_waitcnt vmcnt(8) lgkmcnt(0)
	s_setprio 1
	s_barrier
; #define PG8_STAGE(bufoff, gbase, voff) do { _Pragma("unroll") for (int _i = 0; _i < 2; ++_i) \
;         __builtin_amdgcn_global_load_lds((const unsigned*)((const char*)(gbase) + (voff)[_i]), (PG8_LAS unsigned*)(lds + (bufoff) + ldsw + _i * 8192), 16, 0, 0); } while (0)
; #define PG8_LDA(dst, b, h) do { _Pragma("unroll") for (int m = 0; m < 4; ++m) _Pragma("unroll") for (int k = 0; k < 2; ++k) dst[m][k] = *(const PG8_LAS bf16x8*)(lds + PG8_SA(b, h) + aoff + m * 2048 + k * 1024); } while (0)
; #define PG8_LDB(dst, b, h) do { _Pragma("unroll") for (int n = 0; n < 2; ++n) _Pragma("unroll") for (int k = 0; k < 2; ++k) dst[n][k] = *(const PG8_LAS bf16x8*)(lds + PG8_SB(b, h) + boff + n * 2048 + k * 1024); } while (0)
; #define PG8_MMA(ai, bj, At, Bt) do { __builtin_amdgcn_s_setprio(1); _Pragma("unroll") for (int m = 0; m < 4; ++m) _Pragma("unroll") for (int n = 0; n < 2; ++n) _Pragma("unroll") for (int k = 0; k < 2; ++k) \
;         acc[ai][bj][m][n] = __builtin_amdgcn_mfma_f32_16x16x32_bf16(Bt[n][k], At[m][k], acc[ai][bj][m][n], 0, 0, 0); __builtin_amdgcn_s_setprio(0); } while (0)
; #define PG8_WAIT_V(n) asm volatile("s_waitcnt vmcnt(" #n ")" ::: "memory")
; #define PG8_WAIT_L(n) asm volatile("s_waitcnt lgkmcnt(" #n ")" ::: "memory")
; #define PG8_BAR __builtin_amdgcn_s_barrier()
; #define PG8_SCHED __builtin_amdgcn_sched_barrier(0)
; template <class Epi, class Sched, bool ALIGN_EPI = false, bool SP2 = false>
; __device__ __forceinline__ void gemm_phase(PG8_LAS unsigned char* lds, const Gemm g, const Sched& S, const Epi& E) {
;     ...
;             PG8_WAIT_V(8); PG8_WAIT_L(0); PG8_BAR; PG8_MMA(1, 0, At, B0); PG8_MMA(1, 1, At, B1); PG8_BAR; PG8_SCHED;
;             PG8_LDB(B0, 1, 0); PG8_LDB(B1, 1, 1); PG8_SCHED; PG8_LDA(At, 1, 0); PG8_STAGE(PG8_SA(0, 1), a2 + hstep, voffA);
;             PG8_WAIT_V(8); PG8_WAIT_L(0); PG8_BAR; PG8_MMA(0, 0, At, B0); PG8_MMA(0, 1, At, B1); PG8_BAR; PG8_SCHED;
	v_mfma_f32_16x16x32_bf16 v[62:65], v[152:155], v[190:193], v[62:65]
	v_mfma_f32_16x16x32_bf16 v[58:61], v[160:163], v[190:193], v[58:61]
	v_mfma_f32_16x16x32_bf16 v[46:49], v[152:155], v[198:201], v[46:49]
	v_mfma_f32_16x16x32_bf16 v[42:45], v[160:163], v[198:201], v[42:45]
	v_mfma_f32_16x16x32_bf16 v[30:33], v[152:155], v[206:209], v[30:33]
	v_mfma_f32_16x16x32_bf16 v[26:29], v[160:163], v[206:209], v[26:29]
	v_mfma_f32_16x16x32_bf16 v[14:17], v[152:155], v[214:217], v[14:17]
	v_mfma_f32_16x16x32_bf16 v[10:13], v[160:163], v[214:217], v[10:13]
	v_mfma_f32_16x16x32_bf16 v[62:65], v[156:159], v[194:197], v[62:65]
	v_mfma_f32_16x16x32_bf16 v[58:61], v[164:167], v[194:197], v[58:61]
	v_mfma_f32_16x16x32_bf16 v[46:49], v[156:159], v[202:205], v[46:49]
	v_mfma_f32_16x16x32_bf16 v[42:45], v[164:167], v[202:205], v[42:45]
	v_mfma_f32_16x16x32_bf16 v[30:33], v[156:159], v[210:213], v[30:33]
	v_mfma_f32_16x16x32_bf16 v[26:29], v[164:167], v[210:213], v[26:29]
	v_mfma_f32_16x16x32_bf16 v[14:17], v[156:159], v[224:227], v[14:17]
	v_mfma_f32_16x16x32_bf16 v[10:13], v[164:167], v[224:227], v[10:13]
	v_mfma_f32_16x16x32_bf16 v[54:57], v[168:171], v[190:193], v[54:57]
	v_mfma_f32_16x16x32_bf16 v[50:53], v[182:185], v[190:193], v[50:53]
	v_mfma_f32_16x16x32_bf16 v[38:41], v[168:171], v[198:201], v[38:41]
	v_mfma_f32_16x16x32_bf16 v[34:37], v[182:185], v[198:201], v[34:37]
	v_mfma_f32_16x16x32_bf16 v[22:25], v[168:171], v[206:209], v[22:25]
	v_mfma_f32_16x16x32_bf16 v[18:21], v[182:185], v[206:209], v[18:21]
	v_mfma_f32_16x16x32_bf16 v[6:9], v[168:171], v[214:217], v[6:9]
	v_mfma_f32_16x16x32_bf16 v[2:5], v[182:185], v[214:217], v[2:5]
	v_mfma_f32_16x16x32_bf16 v[54:57], v[172:175], v[194:197], v[54:57]
	v_mfma_f32_16x16x32_bf16 v[50:53], v[186:189], v[194:197], v[50:53]
	v_mfma_f32_16x16x32_bf16 v[38:41], v[172:175], v[202:205], v[38:41]
	v_mfma_f32_16x16x32_bf16 v[34:37], v[186:189], v[202:205], v[34:37]
	v_mfma_f32_16x16x32_bf16 v[22:25], v[172:175], v[210:213], v[22:25]
	v_mfma_f32_16x16x32_bf16 v[18:21], v[186:189], v[210:213], v[18:21]
	v_mfma_f32_16x16x32_bf16 v[6:9], v[172:175], v[224:227], v[6:9]
	v_mfma_f32_16x16x32_bf16 v[2:5], v[186:189], v[224:227], v[2:5]
	s_setprio 0
	s_barrier
	s_add_i32 s48, 0, 0x18000
	s_add_i32 s91, 0, 0x1c000
	v_add_u32_e32 v164, s48, v179
	v_add_u32_e32 v186, s91, v179
	ds_read_b128 v[152:155], v164
	ds_read_b128 v[156:159], v164 offset:1024
	ds_read_b128 v[160:163], v164 offset:2048
	ds_read_b128 v[164:167], v164 offset:3072
	ds_read_b128 v[168:171], v186
	ds_read_b128 v[172:175], v186 offset:1024
	ds_read_b128 v[182:185], v186 offset:2048
	ds_read_b128 v[186:189], v186 offset:3072
	s_add_u32 s30, s30, 0x80000
	s_addc_u32 s31, s31, 0
	s_mov_b32 m0, s82
	v_lshl_add_u64 v[228:229], s[30:31], 0, v[0:1]
	ds_read_b128 v[190:193], v181 offset:32768
	ds_read_b128 v[194:197], v181 offset:33792
	ds_read_b128 v[198:201], v181 offset:34816
	ds_read_b128 v[202:205], v181 offset:35840
	ds_read_b128 v[206:209], v181 offset:36864
	ds_read_b128 v[210:213], v181 offset:37888
	ds_read_b128 v[214:217], v181 offset:38912
	ds_read_b128 v[224:227], v181 offset:39936
	global_load_lds_dwordx4 v[228:229], off
	v_lshl_add_u64 v[228:229], s[30:31], 0, v[126:127]
	s_mov_b32 m0, s83
	s_nop 0
	global_load_lds_dwordx4 v[228:229], off
	s_waitcnt vmcnt(8) lgkmcnt(0)
	s_setprio 1
	s_barrier
	v_mfma_f32_16x16x32_bf16 v[74:77], v[152:155], v[190:193], v[74:77]
	v_mfma_f32_16x16x32_bf16 v[78:81], v[160:163], v[190:193], v[78:81]
	v_mfma_f32_16x16x32_bf16 v[102:105], v[152:155], v[198:201], v[102:105]
	v_mfma_f32_16x16x32_bf16 v[106:109], v[160:163], v[198:201], v[106:109]
	v_mfma_f32_16x16x32_bf16 v[122:125], v[152:155], v[206:209], v[122:125]
	v_mfma_f32_16x16x32_bf16 v[144:147], v[160:163], v[206:209], v[144:147]
	v_mfma_f32_16x16x32_bf16 v[90:93], v[152:155], v[214:217], v[90:93]
	v_mfma_f32_16x16x32_bf16 v[86:89], v[160:163], v[214:217], v[86:89]
	v_mfma_f32_16x16x32_bf16 v[74:77], v[156:159], v[194:197], v[74:77]
	v_mfma_f32_16x16x32_bf16 v[78:81], v[164:167], v[194:197], v[78:81]
	v_mfma_f32_16x16x32_bf16 v[102:105], v[156:159], v[202:205], v[102:105]
	v_mfma_f32_16x16x32_bf16 v[106:109], v[164:167], v[202:205], v[106:109]
	v_mfma_f32_16x16x32_bf16 v[122:125], v[156:159], v[210:213], v[122:125]
	v_mfma_f32_16x16x32_bf16 v[144:147], v[164:167], v[210:213], v[144:147]
	v_mfma_f32_16x16x32_bf16 v[90:93], v[156:159], v[224:227], v[90:93]
	v_mfma_f32_16x16x32_bf16 v[86:89], v[164:167], v[224:227], v[86:89]
	v_mfma_f32_16x16x32_bf16 v[82:85], v[168:171], v[190:193], v[82:85]
	v_mfma_f32_16x16x32_bf16 v[94:97], v[182:185], v[190:193], v[94:97]
	v_mfma_f32_16x16x32_bf16 v[110:113], v[168:171], v[198:201], v[110:113]
	v_mfma_f32_16x16x32_bf16 v[118:121], v[182:185], v[198:201], v[118:121]
	v_mfma_f32_16x16x32_bf16 v[114:117], v[168:171], v[206:209], v[114:117]
	v_mfma_f32_16x16x32_bf16 v[98:101], v[182:185], v[206:209], v[98:101]
	v_mfma_f32_16x16x32_bf16 v[70:73], v[168:171], v[214:217], v[70:73]
	v_mfma_f32_16x16x32_bf16 v[66:69], v[182:185], v[214:217], v[66:69]
	v_mfma_f32_16x16x32_bf16 v[82:85], v[172:175], v[194:197], v[82:85]
	v_mfma_f32_16x16x32_bf16 v[94:97], v[186:189], v[194:197], v[94:97]
	v_mfma_f32_16x16x32_bf16 v[110:113], v[172:175], v[202:205], v[110:113]
	v_mfma_f32_16x16x32_bf16 v[118:121], v[186:189], v[202:205], v[118:121]
	v_mfma_f32_16x16x32_bf16 v[114:117], v[172:175], v[210:213], v[114:117]
	v_mfma_f32_16x16x32_bf16 v[98:101], v[186:189], v[210:213], v[98:101]
	v_mfma_f32_16x16x32_bf16 v[70:73], v[172:175], v[224:227], v[70:73]
	v_mfma_f32_16x16x32_bf16 v[66:69], v[186:189], v[224:227], v[66:69]
	s_setprio 0
	s_barrier
; #define PG8_STAGE(bufoff, gbase, voff) do { _Pragma("unroll") for (int _i = 0; _i < 2; ++_i) \
;         __builtin_amdgcn_global_load_lds((const unsigned*)((const char*)(gbase) + (voff)[_i]), (PG8_LAS unsigned*)(lds + (bufoff) + ldsw + _i * 8192), 16, 0, 0); } while (0)
; #define PG8_LDA(dst, b, h) do { _Pragma("unroll") for (int m = 0; m < 4; ++m) _Pragma("unroll") for (int k = 0; k < 2; ++k) dst[m][k] = *(const PG8_LAS bf16x8*)(lds + PG8_SA(b, h) + aoff + m * 2048 + k * 1024); } while (0)
; #define PG8_MMA(ai, bj, At, Bt) do { __builtin_amdgcn_s_setprio(1); _Pragma("unroll") for (int m = 0; m < 4; ++m) _Pragma("unroll") for (int n = 0; n < 2; ++n) _Pragma("unroll") for (int k = 0; k < 2; ++k) \
;         acc[ai][bj][m][n] = __builtin_amdgcn_mfma_f32_16x16x32_bf16(Bt[n][k], At[m][k], acc[ai][bj][m][n], 0, 0, 0); __builtin_amdgcn_s_setprio(0); } while (0)
; #define PG8_WAIT_V(n) asm volatile("s_waitcnt vmcnt(" #n ")" ::: "memory")
; #define PG8_WAIT_L(n) asm volatile("s_waitcnt lgkmcnt(" #n ")" ::: "memory")
; #define PG8_BAR __builtin_amdgcn_s_barrier()
; #define PG8_SCHED __builtin_amdgcn_sched_barrier(0)
; template <class Epi, class Sched, bool ALIGN_EPI = false, bool SP2 = false>
; __device__ __forceinline__ void gemm_phase(PG8_LAS unsigned char* lds, const Gemm g, const Sched& S, const Epi& E) {
;     ...
;             PG8_LDA(At, 1, 1); PG8_STAGE(PG8_SB(1, 0), b3, voffB); PG8_STAGE(PG8_SB(1, 1), b3 + hstep, voffB); PG8_STAGE(PG8_SA(1, 0), a3, voffA);
;             PG8_WAIT_V(8); PG8_WAIT_L(0); PG8_BAR; PG8_MMA(1, 0, At, B0); PG8_MMA(1, 1, At, B1); PG8_BAR; PG8_SCHED;
;     ...
;         if constexpr (ALIGN_EPI) { if (wr == 0) PG8_BAR; }
	s_add_i32 s30, s48, s42
	v_lshl_add_u64 v[176:177], v[176:177], 0, s[64:65]
	s_mov_b32 m0, s30
	ds_read_b128 v[190:193], v181 offset:49152
	ds_read_b128 v[194:197], v181 offset:50176
	ds_read_b128 v[198:201], v181 offset:51200
	ds_read_b128 v[202:205], v181 offset:52224
	ds_read_b128 v[206:209], v181 offset:53248
	ds_read_b128 v[210:213], v181 offset:54272
	ds_read_b128 v[214:217], v181 offset:55296
	ds_read_b128 v[224:227], v181 offset:56320
	global_load_lds_dwordx4 v[176:177], off
	s_add_i32 m0, s30, 0x2000
	s_add_u32 s28, s28, 0x80080
	v_lshl_add_u64 v[176:177], v[218:219], 0, s[64:65]
	s_addc_u32 s29, s29, 0
	s_add_i32 s30, s91, s42
	global_load_lds_dwordx4 v[176:177], off
	v_lshl_add_u64 v[176:177], s[28:29], 0, v[0:1]
	s_mov_b32 m0, s30
	s_nop 0
	global_load_lds_dwordx4 v[176:177], off
	v_lshl_add_u64 v[176:177], s[28:29], 0, v[126:127]
	s_add_i32 m0, s30, 0x2000
	s_nop 0
	global_load_lds_dwordx4 v[176:177], off
	v_lshl_add_u64 v[176:177], v[220:221], 0, s[64:65]
	s_mov_b32 m0, s86
	s_nop 0
	global_load_lds_dwordx4 v[176:177], off
	v_lshl_add_u64 v[176:177], v[222:223], 0, s[64:65]
	s_mov_b32 m0, s87
	s_nop 0
	global_load_lds_dwordx4 v[176:177], off
	s_waitcnt vmcnt(8) lgkmcnt(0)
	s_setprio 1
	s_barrier
	v_mfma_f32_16x16x32_bf16 v[62:65], v[152:155], v[190:193], v[62:65]
	v_mfma_f32_16x16x32_bf16 v[58:61], v[160:163], v[190:193], v[58:61]
	v_mfma_f32_16x16x32_bf16 v[46:49], v[152:155], v[198:201], v[46:49]
	v_mfma_f32_16x16x32_bf16 v[42:45], v[160:163], v[198:201], v[42:45]
	v_mfma_f32_16x16x32_bf16 v[30:33], v[152:155], v[206:209], v[30:33]
	v_mfma_f32_16x16x32_bf16 v[26:29], v[160:163], v[206:209], v[26:29]
	v_mfma_f32_16x16x32_bf16 v[14:17], v[152:155], v[214:217], v[14:17]
	v_mfma_f32_16x16x32_bf16 v[10:13], v[160:163], v[214:217], v[10:13]
	v_mfma_f32_16x16x32_bf16 v[62:65], v[156:159], v[194:197], v[62:65]
	v_mfma_f32_16x16x32_bf16 v[58:61], v[164:167], v[194:197], v[58:61]
	v_mfma_f32_16x16x32_bf16 v[46:49], v[156:159], v[202:205], v[46:49]
	v_mfma_f32_16x16x32_bf16 v[42:45], v[164:167], v[202:205], v[42:45]
	v_mfma_f32_16x16x32_bf16 v[30:33], v[156:159], v[210:213], v[30:33]
	v_mfma_f32_16x16x32_bf16 v[26:29], v[164:167], v[210:213], v[26:29]
	v_mfma_f32_16x16x32_bf16 v[14:17], v[156:159], v[224:227], v[14:17]
	v_mfma_f32_16x16x32_bf16 v[10:13], v[164:167], v[224:227], v[10:13]
	v_mfma_f32_16x16x32_bf16 v[54:57], v[168:171], v[190:193], v[54:57]
	v_mfma_f32_16x16x32_bf16 v[50:53], v[182:185], v[190:193], v[50:53]
	v_mfma_f32_16x16x32_bf16 v[38:41], v[168:171], v[198:201], v[38:41]
	v_mfma_f32_16x16x32_bf16 v[34:37], v[182:185], v[198:201], v[34:37]
	v_mfma_f32_16x16x32_bf16 v[22:25], v[168:171], v[206:209], v[22:25]
	v_mfma_f32_16x16x32_bf16 v[18:21], v[182:185], v[206:209], v[18:21]
	v_mfma_f32_16x16x32_bf16 v[6:9], v[168:171], v[214:217], v[6:9]
	v_mfma_f32_16x16x32_bf16 v[2:5], v[182:185], v[214:217], v[2:5]
	v_mfma_f32_16x16x32_bf16 v[54:57], v[172:175], v[194:197], v[54:57]
	v_mfma_f32_16x16x32_bf16 v[50:53], v[186:189], v[194:197], v[50:53]
	v_mfma_f32_16x16x32_bf16 v[38:41], v[172:175], v[202:205], v[38:41]
	v_mfma_f32_16x16x32_bf16 v[34:37], v[186:189], v[202:205], v[34:37]
	v_mfma_f32_16x16x32_bf16 v[22:25], v[172:175], v[210:213], v[22:25]
	v_mfma_f32_16x16x32_bf16 v[18:21], v[186:189], v[210:213], v[18:21]
	v_mfma_f32_16x16x32_bf16 v[6:9], v[172:175], v[224:227], v[6:9]
	v_mfma_f32_16x16x32_bf16 v[2:5], v[186:189], v[224:227], v[2:5]
	s_setprio 0
	s_barrier
	s_add_i32 s81, s81, 2
	s_add_u32 s0, s0, 0x100
	s_addc_u32 s1, s1, 0
	s_add_u32 s41, s41, 0x100
	s_addc_u32 s67, s67, 0
	s_cmp_gt_u32 s81, 29
	s_cbranch_scc0 .LBB0_910
	s_and_b64 vcc, exec, s[18:19]
	s_cbranch_vccz .LBB0_913
	s_barrier

; #define PG8_STAGE(bufoff, gbase, voff) do { _Pragma("unroll") for (int _i = 0; _i < 2; ++_i) \
;         __builtin_amdgcn_global_load_lds((const unsigned*)((const char*)(gbase) + (voff)[_i]), (PG8_LAS unsigned*)(lds + (bufoff) + ldsw + _i * 8192), 16, 0, 0); } while (0)
; #define PG8_LDA(dst, b, h) do { _Pragma("unroll") for (int m = 0; m < 4; ++m) _Pragma("unroll") for (int k = 0; k < 2; ++k) dst[m][k] = *(const PG8_LAS bf16x8*)(lds + PG8_SA(b, h) + aoff + m * 2048 + k * 1024); } while (0)
; #define PG8_LDB(dst, b, h) do { _Pragma("unroll") for (int n = 0; n < 2; ++n) _Pragma("unroll") for (int k = 0; k < 2; ++k) dst[n][k] = *(const PG8_LAS bf16x8*)(lds + PG8_SB(b, h) + boff + n * 2048 + k * 1024); } while (0)
; #define PG8_MMA(ai, bj, At, Bt) do { __builtin_amdgcn_s_setprio(1); _Pragma("unroll") for (int m = 0; m < 4; ++m) _Pragma("unroll") for (int n = 0; n < 2; ++n) _Pragma("unroll") for (int k = 0; k < 2; ++k) \
;         acc[ai][bj][m][n] = __builtin_amdgcn_mfma_f32_16x16x32_bf16(Bt[n][k], At[m][k], acc[ai][bj][m][n], 0, 0, 0); __builtin_amdgcn_s_setprio(0); } while (0)
; #define PG8_WAIT_V(n) asm volatile("s_waitcnt vmcnt(" #n ")" ::: "memory")
; #define PG8_WAIT_L(n) asm volatile("s_waitcnt lgkmcnt(" #n ")" ::: "memory")
; template <class Epi, class Sched, bool ALIGN_EPI = false, bool SP2 = false>
; __device__ __forceinline__ void gemm_phase(PG8_LAS unsigned char* lds, const Gemm g, const Sched& S, const Epi& E) {
;     ...
;             const bool last = (t == nt - 2);
;             const char* a1 = cA + (size_t)(t + 1) * kstep;
;             const char* a2 = last ? nA : cA + (size_t)(t + 2) * kstep; const char* b2 = last ? nB : cB + (size_t)(t + 2) * kstep;
;             const char* a3 = a2 + kstep; const char* b3 = b2 + kstep;
;             if (last && has_next) S.a_ready(nxt);
;             if constexpr (SP2) {
;             PG8_LDB(B0, 0, 0); PG8_LDB(B1, 0, 1); PG8_SCHED; PG8_LDA(At, 0, 0); PG8_STAGE(PG8_SA(1, 1), a1 + hstep, voffA);
;             PG8_WAIT_V(8); PG8_WAIT_L(0); PG8_BAR; PG8_MMA(0, 0, At, B0); PG8_MMA(0, 1, At, B1); PG8_BAR; PG8_SCHED;
;             PG8_LDA(At, 0, 1); PG8_STAGE(PG8_SB(0, 0), b2, voffB); PG8_STAGE(PG8_SB(0, 1), b2 + hstep, voffB); PG8_STAGE(PG8_SA(0, 0), a2, voffA);
;             PG8_WAIT_V(8); PG8_WAIT_L(0); PG8_BAR; PG8_MMA(1, 0, At, B0); PG8_MMA(1, 1, At, B1); PG8_BAR; PG8_SCHED;
.LBB0_963:
	s_add_u32 s24, s0, 0xfff80080
	s_addc_u32 s25, s1, -1
	s_add_i32 s43, 0, 0x10000
	s_cmp_eq_u32 s42, 28
	s_cselect_b32 s27, s13, s25
	s_cselect_b32 s26, s17, s24
	s_cselect_b32 s25, s19, s41
	s_cselect_b32 s24, s29, s40
	s_add_i32 s48, 0, 0x14000
	v_add_u32_e32 v164, s43, v197
	v_add_u32_e32 v180, s48, v197
	ds_read_b128 v[152:155], v164
	ds_read_b128 v[156:159], v164 offset:1024
	ds_read_b128 v[160:163], v164 offset:2048
	ds_read_b128 v[164:167], v164 offset:3072
	ds_read_b128 v[168:171], v180
	ds_read_b128 v[172:175], v180 offset:1024
	ds_read_b128 v[176:179], v180 offset:2048
	ds_read_b128 v[180:183], v180 offset:3072
	v_lshl_add_u64 v[220:221], s[0:1], 0, v[148:149]
	s_add_i32 m0, s31, 0xc000
	ds_read_b128 v[184:187], v199
	ds_read_b128 v[188:191], v199 offset:1024
	ds_read_b128 v[192:195], v199 offset:2048
	ds_read_b128 v[200:203], v199 offset:3072
	ds_read_b128 v[204:207], v199 offset:4096
	ds_read_b128 v[208:211], v199 offset:5120
	ds_read_b128 v[212:215], v199 offset:6144
	ds_read_b128 v[216:219], v199 offset:7168
	global_load_lds_dwordx4 v[220:221], off
	v_lshl_add_u64 v[220:221], s[0:1], 0, v[150:151]
	s_add_i32 m0, s31, 0xe000
	s_nop 0
	global_load_lds_dwordx4 v[220:221], off
	s_waitcnt vmcnt(8) lgkmcnt(0)
	s_setprio 1
	s_barrier
	v_mfma_f32_16x16x32_bf16 v[144:147], v[152:155], v[184:187], v[144:147]
	v_mfma_f32_16x16x32_bf16 v[122:125], v[160:163], v[184:187], v[122:125]
	v_mfma_f32_16x16x32_bf16 v[110:113], v[152:155], v[192:195], v[110:113]
	v_mfma_f32_16x16x32_bf16 v[106:109], v[160:163], v[192:195], v[106:109]
	v_mfma_f32_16x16x32_bf16 v[94:97], v[152:155], v[204:207], v[94:97]
	v_mfma_f32_16x16x32_bf16 v[90:93], v[160:163], v[204:207], v[90:93]
	v_mfma_f32_16x16x32_bf16 v[78:81], v[152:155], v[212:215], v[78:81]
	v_mfma_f32_16x16x32_bf16 v[74:77], v[160:163], v[212:215], v[74:77]
	v_mfma_f32_16x16x32_bf16 v[144:147], v[156:159], v[188:191], v[144:147]
	v_mfma_f32_16x16x32_bf16 v[122:125], v[164:167], v[188:191], v[122:125]
	v_mfma_f32_16x16x32_bf16 v[110:113], v[156:159], v[200:203], v[110:113]
	v_mfma_f32_16x16x32_bf16 v[106:109], v[164:167], v[200:203], v[106:109]
	v_mfma_f32_16x16x32_bf16 v[94:97], v[156:159], v[208:211], v[94:97]
	v_mfma_f32_16x16x32_bf16 v[90:93], v[164:167], v[208:211], v[90:93]
	v_mfma_f32_16x16x32_bf16 v[78:81], v[156:159], v[216:219], v[78:81]
	v_mfma_f32_16x16x32_bf16 v[74:77], v[164:167], v[216:219], v[74:77]
	v_mfma_f32_16x16x32_bf16 v[118:121], v[168:171], v[184:187], v[118:121]
	v_mfma_f32_16x16x32_bf16 v[114:117], v[176:179], v[184:187], v[114:117]
	v_mfma_f32_16x16x32_bf16 v[102:105], v[168:171], v[192:195], v[102:105]
	v_mfma_f32_16x16x32_bf16 v[98:101], v[176:179], v[192:195], v[98:101]
	v_mfma_f32_16x16x32_bf16 v[86:89], v[168:171], v[204:207], v[86:89]
	v_mfma_f32_16x16x32_bf16 v[82:85], v[176:179], v[204:207], v[82:85]
	v_mfma_f32_16x16x32_bf16 v[70:73], v[168:171], v[212:215], v[70:73]
	v_mfma_f32_16x16x32_bf16 v[66:69], v[176:179], v[212:215], v[66:69]
	v_mfma_f32_16x16x32_bf16 v[118:121], v[172:175], v[188:191], v[118:121]
	v_mfma_f32_16x16x32_bf16 v[114:117], v[180:183], v[188:191], v[114:117]
	v_mfma_f32_16x16x32_bf16 v[102:105], v[172:175], v[200:203], v[102:105]
	v_mfma_f32_16x16x32_bf16 v[98:101], v[180:183], v[200:203], v[98:101]
	v_mfma_f32_16x16x32_bf16 v[86:89], v[172:175], v[208:211], v[86:89]
	v_mfma_f32_16x16x32_bf16 v[82:85], v[180:183], v[208:211], v[82:85]
	v_mfma_f32_16x16x32_bf16 v[70:73], v[172:175], v[216:219], v[70:73]
	v_mfma_f32_16x16x32_bf16 v[66:69], v[180:183], v[216:219], v[66:69]
	s_setprio 0
	s_barrier
	s_add_i32 s43, s43, s30
	v_lshl_add_u64 v[220:221], s[24:25], 0, v[0:1]
	s_mov_b32 m0, s43
	ds_read_b128 v[184:187], v199 offset:16384
	ds_read_b128 v[188:191], v199 offset:17408
	ds_read_b128 v[192:195], v199 offset:18432
	ds_read_b128 v[200:203], v199 offset:19456
	ds_read_b128 v[204:207], v199 offset:20480
	ds_read_b128 v[208:211], v199 offset:21504
	ds_read_b128 v[212:215], v199 offset:22528
	ds_read_b128 v[216:219], v199 offset:23552
	global_load_lds_dwordx4 v[220:221], off
	s_add_i32 m0, s43, 0x2000
	s_add_u32 vcc_lo, s24, 0x80000
	v_lshl_add_u64 v[222:223], s[24:25], 0, v[126:127]
	s_addc_u32 vcc_hi, s25, 0
	s_add_i32 s43, s48, s30
	global_load_lds_dwordx4 v[222:223], off
	v_lshl_add_u64 v[224:225], vcc, 0, v[0:1]
	s_mov_b32 m0, s43
	v_lshl_add_u64 v[226:227], s[26:27], 0, v[126:127]
	global_load_lds_dwordx4 v[224:225], off
	v_lshl_add_u64 v[224:225], vcc, 0, v[126:127]
	s_add_i32 m0, s43, 0x2000
	s_nop 0
	global_load_lds_dwordx4 v[224:225], off
	v_lshl_add_u64 v[224:225], s[26:27], 0, v[0:1]
	s_mov_b32 m0, s31
	s_nop 0
	global_load_lds_dwordx4 v[224:225], off
	s_mov_b32 m0, s34
	s_nop 0
	global_load_lds_dwordx4 v[226:227], off
	s_waitcnt vmcnt(8) lgkmcnt(0)
	s_setprio 1
	s_barrier
; #define PG8_STAGE(bufoff, gbase, voff) do { _Pragma("unroll") for (int _i = 0; _i < 2; ++_i) \
;         __builtin_amdgcn_global_load_lds((const unsigned*)((const char*)(gbase) + (voff)[_i]), (PG8_LAS unsigned*)(lds + (bufoff) + ldsw + _i * 8192), 16, 0, 0); } while (0)
; #define PG8_LDA(dst, b, h) do { _Pragma("unroll") for (int m = 0; m < 4; ++m) _Pragma("unroll") for (int k = 0; k < 2; ++k) dst[m][k] = *(const PG8_LAS bf16x8*)(lds + PG8_SA(b, h) + aoff + m * 2048 + k * 1024); } while (0)
; #define PG8_LDB(dst, b, h) do { _Pragma("unroll") for (int n = 0; n < 2; ++n) _Pragma("unroll") for (int k = 0; k < 2; ++k) dst[n][k] = *(const PG8_LAS bf16x8*)(lds + PG8_SB(b, h) + boff + n * 2048 + k * 1024); } while (0)
; #define PG8_MMA(ai, bj, At, Bt) do { __builtin_amdgcn_s_setprio(1); _Pragma("unroll") for (int m = 0; m < 4; ++m) _Pragma("unroll") for (int n = 0; n < 2; ++n) _Pragma("unroll") for (int k = 0; k < 2; ++k) \
;         acc[ai][bj][m][n] = __builtin_amdgcn_mfma_f32_16x16x32_bf16(Bt[n][k], At[m][k], acc[ai][bj][m][n], 0, 0, 0); __builtin_amdgcn_s_setprio(0); } while (0)
; #define PG8_WAIT_V(n) asm volatile("s_waitcnt vmcnt(" #n ")" ::: "memory")
; #define PG8_WAIT_L(n) asm volatile("s_waitcnt lgkmcnt(" #n ")" ::: "memory")
; #define PG8_BAR __builtin_amdgcn_s_barrier()
; #define PG8_SCHED __builtin_amdgcn_sched_barrier(0)
; template <class Epi, class Sched, bool ALIGN_EPI = false, bool SP2 = false>
; __device__ __forceinline__ void gemm_phase(PG8_LAS unsigned char* lds, const Gemm g, const Sched& S, const Epi& E) {
;     ...
;             PG8_WAIT_V(8); PG8_WAIT_L(0); PG8_BAR; PG8_MMA(1, 0, At, B0); PG8_MMA(1, 1, At, B1); PG8_BAR; PG8_SCHED;
;             PG8_LDB(B0, 1, 0); PG8_LDB(B1, 1, 1); PG8_SCHED; PG8_LDA(At, 1, 0); PG8_STAGE(PG8_SA(0, 1), a2 + hstep, voffA);
;             PG8_WAIT_V(8); PG8_WAIT_L(0); PG8_BAR; PG8_MMA(0, 0, At, B0); PG8_MMA(0, 1, At, B1); PG8_BAR; PG8_SCHED;
	v_mfma_f32_16x16x32_bf16 v[62:65], v[152:155], v[184:187], v[62:65]
	v_mfma_f32_16x16x32_bf16 v[58:61], v[160:163], v[184:187], v[58:61]
	v_mfma_f32_16x16x32_bf16 v[46:49], v[152:155], v[192:195], v[46:49]
	v_mfma_f32_16x16x32_bf16 v[42:45], v[160:163], v[192:195], v[42:45]
	v_mfma_f32_16x16x32_bf16 v[30:33], v[152:155], v[204:207], v[30:33]
	v_mfma_f32_16x16x32_bf16 v[26:29], v[160:163], v[204:207], v[26:29]
	v_mfma_f32_16x16x32_bf16 v[14:17], v[152:155], v[212:215], v[14:17]
	v_mfma_f32_16x16x32_bf16 v[10:13], v[160:163], v[212:215], v[10:13]
	v_mfma_f32_16x16x32_bf16 v[62:65], v[156:159], v[188:191], v[62:65]
	v_mfma_f32_16x16x32_bf16 v[58:61], v[164:167], v[188:191], v[58:61]
	v_mfma_f32_16x16x32_bf16 v[46:49], v[156:159], v[200:203], v[46:49]
	v_mfma_f32_16x16x32_bf16 v[42:45], v[164:167], v[200:203], v[42:45]
	v_mfma_f32_16x16x32_bf16 v[30:33], v[156:159], v[208:211], v[30:33]
	v_mfma_f32_16x16x32_bf16 v[26:29], v[164:167], v[208:211], v[26:29]
	v_mfma_f32_16x16x32_bf16 v[14:17], v[156:159], v[216:219], v[14:17]
	v_mfma_f32_16x16x32_bf16 v[10:13], v[164:167], v[216:219], v[10:13]
	v_mfma_f32_16x16x32_bf16 v[54:57], v[168:171], v[184:187], v[54:57]
	v_mfma_f32_16x16x32_bf16 v[50:53], v[176:179], v[184:187], v[50:53]
	v_mfma_f32_16x16x32_bf16 v[38:41], v[168:171], v[192:195], v[38:41]
	v_mfma_f32_16x16x32_bf16 v[34:37], v[176:179], v[192:195], v[34:37]
	v_mfma_f32_16x16x32_bf16 v[22:25], v[168:171], v[204:207], v[22:25]
	v_mfma_f32_16x16x32_bf16 v[18:21], v[176:179], v[204:207], v[18:21]
	v_mfma_f32_16x16x32_bf16 v[6:9], v[168:171], v[212:215], v[6:9]
	v_mfma_f32_16x16x32_bf16 v[2:5], v[176:179], v[212:215], v[2:5]
	v_mfma_f32_16x16x32_bf16 v[54:57], v[172:175], v[188:191], v[54:57]
	v_mfma_f32_16x16x32_bf16 v[50:53], v[180:183], v[188:191], v[50:53]
	v_mfma_f32_16x16x32_bf16 v[38:41], v[172:175], v[200:203], v[38:41]
	v_mfma_f32_16x16x32_bf16 v[34:37], v[180:183], v[200:203], v[34:37]
	v_mfma_f32_16x16x32_bf16 v[22:25], v[172:175], v[208:211], v[22:25]
	v_mfma_f32_16x16x32_bf16 v[18:21], v[180:183], v[208:211], v[18:21]
	v_mfma_f32_16x16x32_bf16 v[6:9], v[172:175], v[216:219], v[6:9]
	v_mfma_f32_16x16x32_bf16 v[2:5], v[180:183], v[216:219], v[2:5]
	s_setprio 0
	s_barrier
	s_add_i32 s43, 0, 0x18000
	s_add_i32 s48, 0, 0x1c000
	v_add_u32_e32 v164, s43, v197
	v_add_u32_e32 v180, s48, v197
	ds_read_b128 v[152:155], v164
	ds_read_b128 v[156:159], v164 offset:1024
	ds_read_b128 v[160:163], v164 offset:2048
	ds_read_b128 v[164:167], v164 offset:3072
	ds_read_b128 v[168:171], v180
	ds_read_b128 v[172:175], v180 offset:1024
	ds_read_b128 v[176:179], v180 offset:2048
	ds_read_b128 v[180:183], v180 offset:3072
	s_add_u32 s26, s26, 0x80000
	s_addc_u32 s27, s27, 0
	s_mov_b32 m0, s35
	v_lshl_add_u64 v[228:229], s[26:27], 0, v[0:1]
	ds_read_b128 v[184:187], v199 offset:32768
	ds_read_b128 v[188:191], v199 offset:33792
	ds_read_b128 v[192:195], v199 offset:34816
	ds_read_b128 v[200:203], v199 offset:35840
	ds_read_b128 v[204:207], v199 offset:36864
	ds_read_b128 v[208:211], v199 offset:37888
	ds_read_b128 v[212:215], v199 offset:38912
	ds_read_b128 v[216:219], v199 offset:39936
	global_load_lds_dwordx4 v[228:229], off
	v_lshl_add_u64 v[228:229], s[26:27], 0, v[126:127]
	s_mov_b32 m0, s76
	s_nop 0
	global_load_lds_dwordx4 v[228:229], off
	s_waitcnt vmcnt(8) lgkmcnt(0)
	s_setprio 1
	s_barrier
	v_mfma_f32_16x16x32_bf16 v[144:147], v[152:155], v[184:187], v[144:147]
	v_mfma_f32_16x16x32_bf16 v[122:125], v[160:163], v[184:187], v[122:125]
	v_mfma_f32_16x16x32_bf16 v[110:113], v[152:155], v[192:195], v[110:113]
	v_mfma_f32_16x16x32_bf16 v[106:109], v[160:163], v[192:195], v[106:109]
	v_mfma_f32_16x16x32_bf16 v[94:97], v[152:155], v[204:207], v[94:97]
	v_mfma_f32_16x16x32_bf16 v[90:93], v[160:163], v[204:207], v[90:93]
	v_mfma_f32_16x16x32_bf16 v[78:81], v[152:155], v[212:215], v[78:81]
	v_mfma_f32_16x16x32_bf16 v[74:77], v[160:163], v[212:215], v[74:77]
	v_mfma_f32_16x16x32_bf16 v[144:147], v[156:159], v[188:191], v[144:147]
	v_mfma_f32_16x16x32_bf16 v[122:125], v[164:167], v[188:191], v[122:125]
	v_mfma_f32_16x16x32_bf16 v[110:113], v[156:159], v[200:203], v[110:113]
	v_mfma_f32_16x16x32_bf16 v[106:109], v[164:167], v[200:203], v[106:109]
	v_mfma_f32_16x16x32_bf16 v[94:97], v[156:159], v[208:211], v[94:97]
	v_mfma_f32_16x16x32_bf16 v[90:93], v[164:167], v[208:211], v[90:93]
	v_mfma_f32_16x16x32_bf16 v[78:81], v[156:159], v[216:219], v[78:81]
	v_mfma_f32_16x16x32_bf16 v[74:77], v[164:167], v[216:219], v[74:77]
	v_mfma_f32_16x16x32_bf16 v[118:121], v[168:171], v[184:187], v[118:121]
	v_mfma_f32_16x16x32_bf16 v[114:117], v[176:179], v[184:187], v[114:117]
	v_mfma_f32_16x16x32_bf16 v[102:105], v[168:171], v[192:195], v[102:105]
	v_mfma_f32_16x16x32_bf16 v[98:101], v[176:179], v[192:195], v[98:101]
	v_mfma_f32_16x16x32_bf16 v[86:89], v[168:171], v[204:207], v[86:89]
	v_mfma_f32_16x16x32_bf16 v[82:85], v[176:179], v[204:207], v[82:85]
	v_mfma_f32_16x16x32_bf16 v[70:73], v[168:171], v[212:215], v[70:73]
	v_mfma_f32_16x16x32_bf16 v[66:69], v[176:179], v[212:215], v[66:69]
	v_mfma_f32_16x16x32_bf16 v[118:121], v[172:175], v[188:191], v[118:121]
	v_mfma_f32_16x16x32_bf16 v[114:117], v[180:183], v[188:191], v[114:117]
	v_mfma_f32_16x16x32_bf16 v[102:105], v[172:175], v[200:203], v[102:105]
	v_mfma_f32_16x16x32_bf16 v[98:101], v[180:183], v[200:203], v[98:101]
	v_mfma_f32_16x16x32_bf16 v[86:89], v[172:175], v[208:211], v[86:89]
	v_mfma_f32_16x16x32_bf16 v[82:85], v[180:183], v[208:211], v[82:85]
	v_mfma_f32_16x16x32_bf16 v[70:73], v[172:175], v[216:219], v[70:73]
	v_mfma_f32_16x16x32_bf16 v[66:69], v[180:183], v[216:219], v[66:69]
	s_setprio 0
	s_barrier
; #define PG8_STAGE(bufoff, gbase, voff) do { _Pragma("unroll") for (int _i = 0; _i < 2; ++_i) \
;         __builtin_amdgcn_global_load_lds((const unsigned*)((const char*)(gbase) + (voff)[_i]), (PG8_LAS unsigned*)(lds + (bufoff) + ldsw + _i * 8192), 16, 0, 0); } while (0)
; #define PG8_LDA(dst, b, h) do { _Pragma("unroll") for (int m = 0; m < 4; ++m) _Pragma("unroll") for (int k = 0; k < 2; ++k) dst[m][k] = *(const PG8_LAS bf16x8*)(lds + PG8_SA(b, h) + aoff + m * 2048 + k * 1024); } while (0)
; #define PG8_MMA(ai, bj, At, Bt) do { __builtin_amdgcn_s_setprio(1); _Pragma("unroll") for (int m = 0; m < 4; ++m) _Pragma("unroll") for (int n = 0; n < 2; ++n) _Pragma("unroll") for (int k = 0; k < 2; ++k) \
;         acc[ai][bj][m][n] = __builtin_amdgcn_mfma_f32_16x16x32_bf16(Bt[n][k], At[m][k], acc[ai][bj][m][n], 0, 0, 0); __builtin_amdgcn_s_setprio(0); } while (0)
; #define PG8_WAIT_V(n) asm volatile("s_waitcnt vmcnt(" #n ")" ::: "memory")
; #define PG8_WAIT_L(n) asm volatile("s_waitcnt lgkmcnt(" #n ")" ::: "memory")
; #define PG8_BAR __builtin_amdgcn_s_barrier()
; #define PG8_SCHED __builtin_amdgcn_sched_barrier(0)
; template <class Epi, class Sched, bool ALIGN_EPI = false, bool SP2 = false>
; __device__ __forceinline__ void gemm_phase(PG8_LAS unsigned char* lds, const Gemm g, const Sched& S, const Epi& E) {
;     ...
;             PG8_LDA(At, 1, 1); PG8_STAGE(PG8_SB(1, 0), b3, voffB); PG8_STAGE(PG8_SB(1, 1), b3 + hstep, voffB); PG8_STAGE(PG8_SA(1, 0), a3, voffA);
;             PG8_WAIT_V(8); PG8_WAIT_L(0); PG8_BAR; PG8_MMA(1, 0, At, B0); PG8_MMA(1, 1, At, B1); PG8_BAR; PG8_SCHED;
;     ...
;         if constexpr (ALIGN_EPI) { if (wr == 0) PG8_BAR; }
	s_add_i32 s26, s43, s30
	v_lshl_add_u64 v[220:221], v[220:221], 0, s[64:65]
	s_mov_b32 m0, s26
	ds_read_b128 v[184:187], v199 offset:49152
	ds_read_b128 v[188:191], v199 offset:50176
	ds_read_b128 v[192:195], v199 offset:51200
	ds_read_b128 v[200:203], v199 offset:52224
	ds_read_b128 v[204:207], v199 offset:53248
	ds_read_b128 v[208:211], v199 offset:54272
	ds_read_b128 v[212:215], v199 offset:55296
	ds_read_b128 v[216:219], v199 offset:56320
	global_load_lds_dwordx4 v[220:221], off
	s_add_i32 m0, s26, 0x2000
	s_add_u32 s24, s24, 0x80080
	v_lshl_add_u64 v[220:221], v[222:223], 0, s[64:65]
	s_addc_u32 s25, s25, 0
	s_add_i32 s26, s48, s30
	global_load_lds_dwordx4 v[220:221], off
	v_lshl_add_u64 v[220:221], s[24:25], 0, v[0:1]
	s_mov_b32 m0, s26
	s_nop 0
	global_load_lds_dwordx4 v[220:221], off
	v_lshl_add_u64 v[220:221], s[24:25], 0, v[126:127]
	s_add_i32 m0, s26, 0x2000
	s_nop 0
	global_load_lds_dwordx4 v[220:221], off
	v_lshl_add_u64 v[220:221], v[224:225], 0, s[64:65]
	s_mov_b32 m0, s82
	s_nop 0
	global_load_lds_dwordx4 v[220:221], off
	v_lshl_add_u64 v[220:221], v[226:227], 0, s[64:65]
	s_mov_b32 m0, s83
	s_nop 0
	global_load_lds_dwordx4 v[220:221], off
	s_waitcnt vmcnt(8) lgkmcnt(0)
	s_setprio 1
	s_barrier
	v_mfma_f32_16x16x32_bf16 v[62:65], v[152:155], v[184:187], v[62:65]
	v_mfma_f32_16x16x32_bf16 v[58:61], v[160:163], v[184:187], v[58:61]
	v_mfma_f32_16x16x32_bf16 v[46:49], v[152:155], v[192:195], v[46:49]
	v_mfma_f32_16x16x32_bf16 v[42:45], v[160:163], v[192:195], v[42:45]
	v_mfma_f32_16x16x32_bf16 v[30:33], v[152:155], v[204:207], v[30:33]
	v_mfma_f32_16x16x32_bf16 v[26:29], v[160:163], v[204:207], v[26:29]
	v_mfma_f32_16x16x32_bf16 v[14:17], v[152:155], v[212:215], v[14:17]
	v_mfma_f32_16x16x32_bf16 v[10:13], v[160:163], v[212:215], v[10:13]
	v_mfma_f32_16x16x32_bf16 v[62:65], v[156:159], v[188:191], v[62:65]
	v_mfma_f32_16x16x32_bf16 v[58:61], v[164:167], v[188:191], v[58:61]
	v_mfma_f32_16x16x32_bf16 v[46:49], v[156:159], v[200:203], v[46:49]
	v_mfma_f32_16x16x32_bf16 v[42:45], v[164:167], v[200:203], v[42:45]
	v_mfma_f32_16x16x32_bf16 v[30:33], v[156:159], v[208:211], v[30:33]
	v_mfma_f32_16x16x32_bf16 v[26:29], v[164:167], v[208:211], v[26:29]
	v_mfma_f32_16x16x32_bf16 v[14:17], v[156:159], v[216:219], v[14:17]
	v_mfma_f32_16x16x32_bf16 v[10:13], v[164:167], v[216:219], v[10:13]
	v_mfma_f32_16x16x32_bf16 v[54:57], v[168:171], v[184:187], v[54:57]
	v_mfma_f32_16x16x32_bf16 v[50:53], v[176:179], v[184:187], v[50:53]
	v_mfma_f32_16x16x32_bf16 v[38:41], v[168:171], v[192:195], v[38:41]
	v_mfma_f32_16x16x32_bf16 v[34:37], v[176:179], v[192:195], v[34:37]
	v_mfma_f32_16x16x32_bf16 v[22:25], v[168:171], v[204:207], v[22:25]
	v_mfma_f32_16x16x32_bf16 v[18:21], v[176:179], v[204:207], v[18:21]
	v_mfma_f32_16x16x32_bf16 v[6:9], v[168:171], v[212:215], v[6:9]
	v_mfma_f32_16x16x32_bf16 v[2:5], v[176:179], v[212:215], v[2:5]
	v_mfma_f32_16x16x32_bf16 v[54:57], v[172:175], v[188:191], v[54:57]
	v_mfma_f32_16x16x32_bf16 v[50:53], v[180:183], v[188:191], v[50:53]
	v_mfma_f32_16x16x32_bf16 v[38:41], v[172:175], v[200:203], v[38:41]
	v_mfma_f32_16x16x32_bf16 v[34:37], v[180:183], v[200:203], v[34:37]
	v_mfma_f32_16x16x32_bf16 v[22:25], v[172:175], v[208:211], v[22:25]
	v_mfma_f32_16x16x32_bf16 v[18:21], v[180:183], v[208:211], v[18:21]
	v_mfma_f32_16x16x32_bf16 v[6:9], v[172:175], v[216:219], v[6:9]
	v_mfma_f32_16x16x32_bf16 v[2:5], v[180:183], v[216:219], v[2:5]
	s_setprio 0
	s_barrier
	s_add_i32 s42, s42, 2
	s_add_u32 s0, s0, 0x100
	s_addc_u32 s1, s1, 0
	s_add_u32 s40, s40, 0x100
	s_addc_u32 s41, s41, 0
	s_cmp_gt_u32 s42, 29
	s_cbranch_scc0 .LBB0_963
	s_and_b64 vcc, exec, s[14:15]
	s_cbranch_vccz .LBB0_966
	s_barrier
